# v20 + P12 top-k: bit search starts below common prefix of lower/upper bounds (group-max min / max) of the 256th key
# speedup vs baseline: 1.0018x; 1.0006x over previous
; #define LAS __attribute__((address_space(3)))
; DI size_t sc_row_off(int b, int s) { const int qb = s >> 7; return ((size_t)(b * 2080 + ((qb * (qb + 1)) >> 1))) * 16384 + (size_t)(s & 127) * ((qb + 1) * 128); }
; DI unsigned f2key(float f) { const unsigned u = __float_as_uint(f); return (u & 0x80000000u) ? ~u : (u | 0x80000000u); }
; template <int NV>
; DI void topk_row(const float* row, int s, LAS int* lst, int lane) {
;     unsigned key[NV];
;     { const unsigned long long ra = (unsigned long long)row; const unsigned rlo = __builtin_amdgcn_readfirstlane((unsigned)ra), rhi = __builtin_amdgcn_readfirstlane((unsigned)(ra >> 32));
;       row = (const float*)(((unsigned long long)rhi << 32) | rlo); }
; #pragma unroll
;     for (int jo = 0; jo < NV / 16; ++jo) { const float* rb = row + jo * 1024;
; #pragma unroll
;         for (int ji = 0; ji < 16; ++ji) { const int j = jo * 16 + ji; const unsigned u = f2key(rb[ji * 64 + lane]); key[j] = (j * 64 + lane <= s) ? u : 0u; } }
; DI void topk_phase(const float* SC, unsigned short* IDX, LAS unsigned char* lds, int tid, int bid, int G) {
;     ...
;         const int b = t >> 13, s = t & 8191; unsigned short* out = IDX + (size_t)t * 256;
;         if (s < 256) {
; #pragma unroll
;             for (int i = 0; i < 4; ++i) { const int j = lane + 64 * i; out[j] = (unsigned short)((j <= s) ? j : 0); }
;         } else {
;             const float* row = SC + sc_row_off(b, s);
;             if (s < 2048) topk_row<32>(row, s, lst, lane);
;             else if (s < 4096) topk_row<64>(row, s, lst, lane);
;             else if (s < 6144) topk_row<96>(row, s, lst, lane);
;             else topk_row<128>(row, s, lst, lane);
.LBB0_1965:
	s_lshr_b32 s1, s85, 7
	s_add_i32 s2, s1, 1
	s_ashr_i32 s0, s8, 13
	s_mul_i32 s1, s2, s1
	s_mulk_i32 s0, 0x820
	s_lshr_b32 s1, s1, 1
	s_add_i32 s0, s1, s0
	s_ashr_i32 s1, s0, 31
	s_lshl_b32 s3, s8, 7
	s_and_b32 s3, s3, 0x3f80
	s_lshl_b64 s[0:1], s[0:1], 16
	s_mul_i32 s2, s2, s3
	s_add_u32 s0, s14, s0
	s_addc_u32 s1, s15, s1
	s_lshl_b32 s2, s2, 2
	s_add_u32 s12, s0, s2
	s_addc_u32 s13, s1, 0
	s_cmpk_gt_u32 s85, 0x7ff
	v_sub_u32_e32 v161, s85, v2
	s_cbranch_scc0 .LBB0_2481
	s_cmpk_gt_u32 s85, 0xfff
	s_cbranch_scc0 .LBB0_2482
	s_cmpk_gt_u32 s85, 0x17ff
	s_cbranch_scc0 .LBB0_2483
	v_lshlrev_b32_e32 v0, 2, v2
	v_lshl_add_u64 v[40:41], s[12:13], 0, v[0:1]
	flat_load_dword v48, v[40:41]
	flat_load_dword v49, v[40:41] offset:256
	flat_load_dword v50, v[40:41] offset:512
	flat_load_dword v51, v[40:41] offset:768
	flat_load_dword v52, v[40:41] offset:1024
	flat_load_dword v53, v[40:41] offset:1280
	flat_load_dword v54, v[40:41] offset:1536
	flat_load_dword v55, v[40:41] offset:1792
	flat_load_dword v56, v[40:41] offset:2048
	flat_load_dword v57, v[40:41] offset:2304
	flat_load_dword v58, v[40:41] offset:2560
	flat_load_dword v59, v[40:41] offset:2816
	flat_load_dword v60, v[40:41] offset:3072
	flat_load_dword v128, v[40:41] offset:3328
	flat_load_dword v129, v[40:41] offset:3584
	flat_load_dword v130, v[40:41] offset:3840
	s_add_u32 s0, s12, 0x1000
	s_addc_u32 s1, s13, 0
	v_lshlrev_b32_e32 v38, 2, v4
	v_mov_b32_e32 v39, v1
	v_lshlrev_b32_e32 v36, 2, v6
	v_mov_b32_e32 v37, v1
	v_lshlrev_b32_e32 v34, 2, v8
	v_mov_b32_e32 v35, v1
	v_lshl_add_u64 v[40:41], s[0:1], 0, v[0:1]
	v_lshl_add_u64 v[42:43], s[0:1], 0, v[38:39]
	v_lshl_add_u64 v[44:45], s[0:1], 0, v[36:37]
	v_lshl_add_u64 v[46:47], s[0:1], 0, v[34:35]
	flat_load_dword v131, v[40:41]
	flat_load_dword v162, v[42:43]
	flat_load_dword v164, v[44:45]
	flat_load_dword v165, v[46:47]
	s_movk_i32 s2, 0x17ff
	s_waitcnt vmcnt(0) lgkmcnt(0)
	v_not_b32_e32 v40, v48
	v_or_b32_e32 v41, 0x80000000, v48
	v_cmp_gt_i32_e32 vcc, 0, v48
	v_not_b32_e32 v42, v49
	v_or_b32_e32 v43, 0x80000000, v49
	v_cndmask_b32_e32 v141, v41, v40, vcc
	v_cmp_gt_i32_e32 vcc, 0, v49
	v_not_b32_e32 v44, v50
	v_or_b32_e32 v45, 0x80000000, v50
	v_cndmask_b32_e32 v140, v43, v42, vcc
	v_cmp_gt_i32_e32 vcc, 0, v50
	v_not_b32_e32 v46, v51
	v_or_b32_e32 v47, 0x80000000, v51
	v_cndmask_b32_e32 v139, v45, v44, vcc
	v_cmp_gt_i32_e32 vcc, 0, v51
	v_not_b32_e32 v61, v52
	v_or_b32_e32 v62, 0x80000000, v52
	v_cndmask_b32_e32 v138, v47, v46, vcc
	v_cmp_gt_i32_e32 vcc, 0, v52
	v_not_b32_e32 v63, v53
	v_or_b32_e32 v132, 0x80000000, v53
	v_cndmask_b32_e32 v137, v62, v61, vcc
	v_cmp_gt_i32_e32 vcc, 0, v53
	v_not_b32_e32 v133, v54
	v_or_b32_e32 v134, 0x80000000, v54
	v_cndmask_b32_e32 v136, v132, v63, vcc
	v_cmp_gt_i32_e32 vcc, 0, v54
	v_not_b32_e32 v163, v55
	v_or_b32_e32 v166, 0x80000000, v55
	v_cndmask_b32_e32 v135, v134, v133, vcc
	v_cmp_gt_i32_e32 vcc, 0, v55
	v_not_b32_e32 v167, v56
	v_or_b32_e32 v168, 0x80000000, v56
	v_cndmask_b32_e32 v134, v166, v163, vcc
	v_cmp_gt_i32_e32 vcc, 0, v56
	v_not_b32_e32 v169, v57
	v_or_b32_e32 v170, 0x80000000, v57
	v_cndmask_b32_e32 v133, v168, v167, vcc
	v_cmp_gt_i32_e32 vcc, 0, v57
	v_not_b32_e32 v171, v58
	v_or_b32_e32 v172, 0x80000000, v58
	v_cndmask_b32_e32 v132, v170, v169, vcc
	v_cmp_gt_i32_e32 vcc, 0, v58
	v_not_b32_e32 v173, v59
	v_or_b32_e32 v174, 0x80000000, v59
	v_cndmask_b32_e32 v251, v172, v171, vcc
	v_cmp_gt_i32_e32 vcc, 0, v59
	v_lshlrev_b32_e32 v62, 2, v10
	v_mov_b32_e32 v63, v1
	v_not_b32_e32 v175, v60
	v_or_b32_e32 v176, 0x80000000, v60
	v_cndmask_b32_e32 v248, v174, v173, vcc
	v_lshl_add_u64 v[40:41], s[0:1], 0, v[62:63]
	v_cmp_gt_i32_e32 vcc, 0, v60
	v_lshlrev_b32_e32 v60, 2, v12
	v_mov_b32_e32 v61, v1
	flat_load_dword v166, v[40:41]
	v_lshl_add_u64 v[40:41], s[0:1], 0, v[60:61]
	flat_load_dword v167, v[40:41]
	v_lshlrev_b32_e32 v58, 2, v14
	v_mov_b32_e32 v59, v1
	v_lshl_add_u64 v[40:41], s[0:1], 0, v[58:59]
	flat_load_dword v168, v[40:41]
	v_lshlrev_b32_e32 v56, 2, v16
	v_mov_b32_e32 v57, v1
	v_lshl_add_u64 v[40:41], s[0:1], 0, v[56:57]
	flat_load_dword v169, v[40:41]
	v_lshlrev_b32_e32 v52, 2, v18
	v_mov_b32_e32 v53, v1
	v_cndmask_b32_e32 v247, v176, v175, vcc
	v_not_b32_e32 v42, v128
	v_or_b32_e32 v43, 0x80000000, v128
	v_cmp_gt_i32_e32 vcc, 0, v128
	v_lshl_add_u64 v[40:41], s[0:1], 0, v[52:53]
	flat_load_dword v170, v[40:41]
	v_cndmask_b32_e32 v253, v43, v42, vcc
	v_not_b32_e32 v42, v129
	v_or_b32_e32 v40, 0x80000000, v129
	v_cmp_gt_i32_e32 vcc, 0, v129
	v_lshlrev_b32_e32 v54, 2, v20
	v_mov_b32_e32 v55, v1
	v_cndmask_b32_e32 v249, v40, v42, vcc
	v_lshl_add_u64 v[40:41], s[0:1], 0, v[54:55]
	flat_load_dword v171, v[40:41]
	v_lshlrev_b32_e32 v50, 2, v22
	v_mov_b32_e32 v51, v1
	v_lshl_add_u64 v[40:41], s[0:1], 0, v[50:51]
	flat_load_dword v172, v[40:41]
	v_lshlrev_b32_e32 v48, 2, v24
	v_mov_b32_e32 v49, v1
	v_lshl_add_u64 v[40:41], s[0:1], 0, v[48:49]
	flat_load_dword v173, v[40:41]
	v_lshlrev_b32_e32 v46, 2, v26
	v_mov_b32_e32 v47, v1
	v_lshl_add_u64 v[40:41], s[0:1], 0, v[46:47]
	flat_load_dword v174, v[40:41]
	v_lshlrev_b32_e32 v44, 2, v28
	v_mov_b32_e32 v45, v1
	v_lshl_add_u64 v[40:41], s[0:1], 0, v[44:45]
	flat_load_dword v175, v[40:41]
	v_not_b32_e32 v42, v130
	v_or_b32_e32 v43, 0x80000000, v130
	v_cmp_gt_i32_e32 vcc, 0, v130
	v_not_b32_e32 v129, v162
	v_or_b32_e32 v130, 0x80000000, v162
	v_cndmask_b32_e32 v252, v43, v42, vcc
	v_not_b32_e32 v42, v131
	v_or_b32_e32 v43, 0x80000000, v131
	v_cmp_gt_i32_e32 vcc, 0, v131
	v_or_b32_e32 v131, 0x80000000, v164
	s_nop 0
	v_cndmask_b32_e32 v128, v43, v42, vcc
	v_lshlrev_b32_e32 v42, 2, v30
	v_mov_b32_e32 v43, v1
	v_lshl_add_u64 v[40:41], s[0:1], 0, v[42:43]
	flat_load_dword v176, v[40:41]
	v_lshlrev_b32_e32 v40, 2, v32
	v_mov_b32_e32 v41, v1
	v_cmp_gt_i32_e32 vcc, 0, v162
	v_lshl_add_u64 v[162:163], s[0:1], 0, v[40:41]
	s_add_u32 s0, s12, 0x2000
	flat_load_dword v177, v[162:163]
	s_addc_u32 s1, s13, 0
	v_lshl_add_u64 v[162:163], s[0:1], 0, v[0:1]
	v_cndmask_b32_e32 v130, v130, v129, vcc
	v_not_b32_e32 v129, v164
	flat_load_dword v178, v[162:163]
	v_cmp_gt_i32_e32 vcc, 0, v164
	v_or_b32_e32 v164, 0x80000000, v165
	v_lshl_add_u64 v[162:163], s[0:1], 0, v[38:39]
	v_cndmask_b32_e32 v131, v131, v129, vcc
	v_not_b32_e32 v129, v165
	v_cmp_gt_i32_e32 vcc, 0, v165
	flat_load_dword v179, v[162:163]
	v_lshl_add_u64 v[162:163], s[0:1], 0, v[36:37]
	v_cndmask_b32_e32 v129, v164, v129, vcc
	s_waitcnt vmcnt(0) lgkmcnt(0)
; DI unsigned f2key(float f) { const unsigned u = __float_as_uint(f); return (u & 0x80000000u) ? ~u : (u | 0x80000000u); }
; template <int NV>
; DI void topk_row(const float* row, int s, LAS int* lst, int lane) {
;     ...
;     for (int jo = 0; jo < NV / 16; ++jo) { const float* rb = row + jo * 1024;
; #pragma unroll
;         for (int ji = 0; ji < 16; ++ji) { const int j = jo * 16 + ji; const unsigned u = f2key(rb[ji * 64 + lane]); key[j] = (j * 64 + lane <= s) ? u : 0u; } }
	v_not_b32_e32 v164, v166
	v_or_b32_e32 v165, 0x80000000, v166
	v_cmp_gt_i32_e32 vcc, 0, v166
	flat_load_dword v180, v[162:163]
	v_not_b32_e32 v162, v167
	v_cndmask_b32_e32 v250, v165, v164, vcc
	v_or_b32_e32 v163, 0x80000000, v167
	v_cmp_gt_i32_e32 vcc, 0, v167
	v_not_b32_e32 v164, v168
	s_nop 0
	v_cndmask_b32_e32 v246, v163, v162, vcc
	v_lshl_add_u64 v[162:163], s[0:1], 0, v[34:35]
	flat_load_dword v165, v[162:163]
	v_or_b32_e32 v162, 0x80000000, v168
	v_cmp_gt_i32_e32 vcc, 0, v168
	v_or_b32_e32 v168, 0x80000000, v170
	s_nop 0
	v_cndmask_b32_e32 v245, v162, v164, vcc
	v_lshl_add_u64 v[162:163], s[0:1], 0, v[62:63]
	v_not_b32_e32 v164, v169
	flat_load_dword v166, v[162:163]
	v_or_b32_e32 v162, 0x80000000, v169
	v_cmp_gt_i32_e32 vcc, 0, v169
	s_nop 1
	v_cndmask_b32_e32 v244, v162, v164, vcc
	v_lshl_add_u64 v[162:163], s[0:1], 0, v[60:61]
	flat_load_dword v167, v[162:163]
	v_lshl_add_u64 v[162:163], s[0:1], 0, v[58:59]
	flat_load_dword v169, v[162:163]
	v_lshl_add_u64 v[162:163], s[0:1], 0, v[56:57]
	v_not_b32_e32 v164, v170
	v_cmp_gt_i32_e32 vcc, 0, v170
	flat_load_dword v170, v[162:163]
	v_lshl_add_u64 v[162:163], s[0:1], 0, v[52:53]
	v_cndmask_b32_e32 v243, v168, v164, vcc
	v_not_b32_e32 v164, v171
	v_or_b32_e32 v168, 0x80000000, v171
	v_cmp_gt_i32_e32 vcc, 0, v171
	flat_load_dword v171, v[162:163]
	v_lshl_add_u64 v[162:163], s[0:1], 0, v[54:55]
	v_cndmask_b32_e32 v242, v168, v164, vcc
	v_not_b32_e32 v164, v172
	v_or_b32_e32 v168, 0x80000000, v172
	v_cmp_gt_i32_e32 vcc, 0, v172
	flat_load_dword v172, v[162:163]
	v_lshl_add_u64 v[162:163], s[0:1], 0, v[50:51]
	v_cndmask_b32_e32 v241, v168, v164, vcc
	v_not_b32_e32 v164, v173
	v_or_b32_e32 v168, 0x80000000, v173
	v_cmp_gt_i32_e32 vcc, 0, v173
	flat_load_dword v173, v[162:163]
	v_lshl_add_u64 v[162:163], s[0:1], 0, v[48:49]
	v_cndmask_b32_e32 v240, v168, v164, vcc
	v_not_b32_e32 v164, v174
	v_or_b32_e32 v168, 0x80000000, v174
	v_cmp_gt_i32_e32 vcc, 0, v174
	flat_load_dword v174, v[162:163]
	v_lshl_add_u64 v[162:163], s[0:1], 0, v[46:47]
	v_cndmask_b32_e32 v239, v168, v164, vcc
	v_not_b32_e32 v164, v175
	v_or_b32_e32 v168, 0x80000000, v175
	v_cmp_gt_i32_e32 vcc, 0, v175
	flat_load_dword v175, v[162:163]
	v_lshl_add_u64 v[162:163], s[0:1], 0, v[44:45]
	v_cndmask_b32_e32 v238, v168, v164, vcc
	v_not_b32_e32 v164, v176
	v_or_b32_e32 v168, 0x80000000, v176
	v_cmp_gt_i32_e32 vcc, 0, v176
	flat_load_dword v176, v[162:163]
	v_lshl_add_u64 v[162:163], s[0:1], 0, v[42:43]
	v_cndmask_b32_e32 v237, v168, v164, vcc
	v_not_b32_e32 v164, v177
	v_or_b32_e32 v168, 0x80000000, v177
	v_cmp_gt_i32_e32 vcc, 0, v177
	flat_load_dword v177, v[162:163]
	v_lshl_add_u64 v[162:163], s[0:1], 0, v[40:41]
	v_cndmask_b32_e32 v236, v168, v164, vcc
	v_not_b32_e32 v164, v178
	v_or_b32_e32 v168, 0x80000000, v178
	v_cmp_gt_i32_e32 vcc, 0, v178
	flat_load_dword v178, v[162:163]
	s_add_u32 s0, s12, 0x3000
	s_addc_u32 s1, s13, 0
	v_cndmask_b32_e32 v235, v168, v164, vcc
	v_not_b32_e32 v164, v179
	v_or_b32_e32 v168, 0x80000000, v179
	v_cmp_gt_i32_e32 vcc, 0, v179
	v_lshl_add_u64 v[162:163], s[0:1], 0, v[0:1]
	s_waitcnt vmcnt(0) lgkmcnt(0)
	v_or_b32_e32 v179, 0x80000000, v165
	v_cndmask_b32_e32 v234, v168, v164, vcc
	flat_load_dword v168, v[162:163]
	v_not_b32_e32 v164, v180
	v_or_b32_e32 v162, 0x80000000, v180
	v_cmp_gt_i32_e32 vcc, 0, v180
	s_nop 1
	v_cndmask_b32_e32 v233, v162, v164, vcc
	v_not_b32_e32 v164, v165
	v_lshl_add_u64 v[162:163], s[0:1], 0, v[38:39]
	v_cmp_gt_i32_e32 vcc, 0, v165
	flat_load_dword v180, v[162:163]
	v_or_b32_e32 v165, 0x80000000, v166
	v_cndmask_b32_e32 v232, v179, v164, vcc
	v_not_b32_e32 v164, v166
	v_lshl_add_u64 v[162:163], s[0:1], 0, v[36:37]
	v_cmp_gt_i32_e32 vcc, 0, v166
	flat_load_dword v179, v[162:163]
	v_not_b32_e32 v162, v167
	v_cndmask_b32_e32 v231, v165, v164, vcc
	v_or_b32_e32 v163, 0x80000000, v167
	v_cmp_gt_i32_e32 vcc, 0, v167
	v_not_b32_e32 v164, v169
	s_nop 0
	v_cndmask_b32_e32 v230, v163, v162, vcc
	v_lshl_add_u64 v[162:163], s[0:1], 0, v[34:35]
	flat_load_dword v165, v[162:163]
	v_or_b32_e32 v162, 0x80000000, v169
	v_cmp_gt_i32_e32 vcc, 0, v169
	s_nop 1
	v_cndmask_b32_e32 v229, v162, v164, vcc
	v_lshl_add_u64 v[162:163], s[0:1], 0, v[62:63]
	v_not_b32_e32 v164, v170
	flat_load_dword v166, v[162:163]
	v_or_b32_e32 v162, 0x80000000, v170
	v_cmp_gt_i32_e32 vcc, 0, v170
	s_nop 1
	v_cndmask_b32_e32 v228, v162, v164, vcc
	v_lshl_add_u64 v[162:163], s[0:1], 0, v[60:61]
	v_not_b32_e32 v164, v171
	flat_load_dword v167, v[162:163]
	v_or_b32_e32 v162, 0x80000000, v171
	v_cmp_gt_i32_e32 vcc, 0, v171
	s_nop 1
	v_cndmask_b32_e32 v227, v162, v164, vcc
	v_lshl_add_u64 v[162:163], s[0:1], 0, v[58:59]
	v_not_b32_e32 v164, v172
	flat_load_dword v169, v[162:163]
	v_or_b32_e32 v162, 0x80000000, v172
	v_cmp_gt_i32_e32 vcc, 0, v172
	s_nop 1
	v_cndmask_b32_e32 v226, v162, v164, vcc
	v_lshl_add_u64 v[162:163], s[0:1], 0, v[56:57]
	v_not_b32_e32 v164, v173
	flat_load_dword v170, v[162:163]
	v_or_b32_e32 v162, 0x80000000, v173
	v_cmp_gt_i32_e32 vcc, 0, v173
	s_nop 1
	v_cndmask_b32_e32 v225, v162, v164, vcc
	v_lshl_add_u64 v[162:163], s[0:1], 0, v[52:53]
	v_not_b32_e32 v164, v174
	flat_load_dword v171, v[162:163]
	v_or_b32_e32 v162, 0x80000000, v174
	v_cmp_gt_i32_e32 vcc, 0, v174
	s_nop 1
	v_cndmask_b32_e32 v224, v162, v164, vcc
	v_lshl_add_u64 v[162:163], s[0:1], 0, v[54:55]
	v_not_b32_e32 v164, v175
	flat_load_dword v172, v[162:163]
	v_or_b32_e32 v162, 0x80000000, v175
	v_cmp_gt_i32_e32 vcc, 0, v175
	s_nop 1
	v_cndmask_b32_e32 v223, v162, v164, vcc
	v_lshl_add_u64 v[162:163], s[0:1], 0, v[50:51]
	flat_load_dword v173, v[162:163]
	v_not_b32_e32 v164, v176
	v_or_b32_e32 v162, 0x80000000, v176
	v_cmp_gt_i32_e32 vcc, 0, v176
	s_nop 1
	v_cndmask_b32_e32 v222, v162, v164, vcc
	v_lshl_add_u64 v[162:163], s[0:1], 0, v[48:49]
	v_not_b32_e32 v164, v177
	flat_load_dword v174, v[162:163]
	v_or_b32_e32 v162, 0x80000000, v177
	v_cmp_gt_i32_e32 vcc, 0, v177
	s_waitcnt vmcnt(0) lgkmcnt(0)
; DI unsigned f2key(float f) { const unsigned u = __float_as_uint(f); return (u & 0x80000000u) ? ~u : (u | 0x80000000u); }
; template <int NV>
; DI void topk_row(const float* row, int s, LAS int* lst, int lane) {
;     ...
;     for (int jo = 0; jo < NV / 16; ++jo) { const float* rb = row + jo * 1024;
; #pragma unroll
;         for (int ji = 0; ji < 16; ++ji) { const int j = jo * 16 + ji; const unsigned u = f2key(rb[ji * 64 + lane]); key[j] = (j * 64 + lane <= s) ? u : 0u; } }
	v_or_b32_e32 v177, 0x80000000, v168
	v_cndmask_b32_e32 v221, v162, v164, vcc
	v_lshl_add_u64 v[162:163], s[0:1], 0, v[46:47]
	v_not_b32_e32 v164, v178
	flat_load_dword v175, v[162:163]
	v_or_b32_e32 v162, 0x80000000, v178
	v_cmp_gt_i32_e32 vcc, 0, v178
	s_nop 1
	v_cndmask_b32_e32 v220, v162, v164, vcc
	v_lshl_add_u64 v[162:163], s[0:1], 0, v[44:45]
	flat_load_dword v176, v[162:163]
	v_lshl_add_u64 v[162:163], s[0:1], 0, v[42:43]
	flat_load_dword v178, v[162:163]
	v_not_b32_e32 v164, v168
	v_cmp_gt_i32_e32 vcc, 0, v168
	v_lshl_add_u64 v[162:163], s[0:1], 0, v[40:41]
	s_add_u32 s0, s12, 0x4000
	v_cndmask_b32_e32 v219, v177, v164, vcc
	flat_load_dword v177, v[162:163]
	s_addc_u32 s1, s13, 0
	v_not_b32_e32 v164, v180
	v_or_b32_e32 v168, 0x80000000, v180
	v_cmp_gt_i32_e32 vcc, 0, v180
	v_lshl_add_u64 v[162:163], s[0:1], 0, v[0:1]
	s_nop 0
	v_cndmask_b32_e32 v218, v168, v164, vcc
	v_not_b32_e32 v164, v179
	flat_load_dword v168, v[162:163]
	v_or_b32_e32 v162, 0x80000000, v179
	v_cmp_gt_i32_e32 vcc, 0, v179
	s_nop 1
	v_cndmask_b32_e32 v217, v162, v164, vcc
	v_lshl_add_u64 v[162:163], s[0:1], 0, v[38:39]
	v_not_b32_e32 v164, v165
	flat_load_dword v179, v[162:163]
	v_or_b32_e32 v162, 0x80000000, v165
	v_cmp_gt_i32_e32 vcc, 0, v165
	s_nop 1
	v_cndmask_b32_e32 v216, v162, v164, vcc
	v_lshl_add_u64 v[162:163], s[0:1], 0, v[36:37]
	v_not_b32_e32 v164, v166
	flat_load_dword v165, v[162:163]
	v_or_b32_e32 v162, 0x80000000, v166
	v_cmp_gt_i32_e32 vcc, 0, v166
	s_nop 1
	v_cndmask_b32_e32 v215, v162, v164, vcc
	v_lshl_add_u64 v[162:163], s[0:1], 0, v[34:35]
	v_not_b32_e32 v164, v167
	flat_load_dword v166, v[162:163]
	v_or_b32_e32 v162, 0x80000000, v167
	v_cmp_gt_i32_e32 vcc, 0, v167
	v_or_b32_e32 v167, 0x80000000, v169
	s_nop 0
	v_cndmask_b32_e32 v214, v162, v164, vcc
	v_lshl_add_u64 v[162:163], s[0:1], 0, v[62:63]
	flat_load_dword v180, v[162:163]
	v_not_b32_e32 v164, v169
	v_cmp_gt_i32_e32 vcc, 0, v169
	v_lshl_add_u64 v[162:163], s[0:1], 0, v[60:61]
	v_or_b32_e32 v169, 0x80000000, v171
	v_cndmask_b32_e32 v213, v167, v164, vcc
	v_not_b32_e32 v164, v170
	flat_load_dword v167, v[162:163]
	v_or_b32_e32 v162, 0x80000000, v170
	v_cmp_gt_i32_e32 vcc, 0, v170
	s_nop 1
	v_cndmask_b32_e32 v212, v162, v164, vcc
	v_lshl_add_u64 v[162:163], s[0:1], 0, v[58:59]
	flat_load_dword v170, v[162:163]
	v_lshl_add_u64 v[162:163], s[0:1], 0, v[56:57]
	v_not_b32_e32 v164, v171
	v_cmp_gt_i32_e32 vcc, 0, v171
	flat_load_dword v171, v[162:163]
	v_lshl_add_u64 v[162:163], s[0:1], 0, v[52:53]
	v_cndmask_b32_e32 v211, v169, v164, vcc
	v_not_b32_e32 v164, v172
	v_or_b32_e32 v169, 0x80000000, v172
	v_cmp_gt_i32_e32 vcc, 0, v172
	flat_load_dword v172, v[162:163]
	v_lshl_add_u64 v[162:163], s[0:1], 0, v[54:55]
	v_cndmask_b32_e32 v210, v169, v164, vcc
	v_not_b32_e32 v164, v173
	v_or_b32_e32 v169, 0x80000000, v173
	v_cmp_gt_i32_e32 vcc, 0, v173
	flat_load_dword v173, v[162:163]
	v_lshl_add_u64 v[162:163], s[0:1], 0, v[50:51]
	v_cndmask_b32_e32 v209, v169, v164, vcc
	v_not_b32_e32 v164, v174
	v_or_b32_e32 v169, 0x80000000, v174
	v_cmp_gt_i32_e32 vcc, 0, v174
	flat_load_dword v174, v[162:163]
	s_waitcnt vmcnt(0) lgkmcnt(0)
	v_not_b32_e32 v162, v176
	v_cndmask_b32_e32 v208, v169, v164, vcc
	v_not_b32_e32 v164, v175
	v_or_b32_e32 v169, 0x80000000, v175
	v_cmp_gt_i32_e32 vcc, 0, v175
	v_or_b32_e32 v163, 0x80000000, v176
	s_nop 0
	v_cndmask_b32_e32 v207, v169, v164, vcc
	v_cmp_gt_i32_e32 vcc, 0, v176
	v_not_b32_e32 v164, v178
	s_nop 0
	v_cndmask_b32_e32 v206, v163, v162, vcc
	v_lshl_add_u64 v[162:163], s[0:1], 0, v[48:49]
	flat_load_dword v169, v[162:163]
	v_or_b32_e32 v162, 0x80000000, v178
	v_cmp_gt_i32_e32 vcc, 0, v178
	s_nop 1
	v_cndmask_b32_e32 v205, v162, v164, vcc
	v_lshl_add_u64 v[162:163], s[0:1], 0, v[46:47]
	v_not_b32_e32 v164, v177
	flat_load_dword v175, v[162:163]
	v_or_b32_e32 v162, 0x80000000, v177
	v_cmp_gt_i32_e32 vcc, 0, v177
	v_or_b32_e32 v177, 0x80000000, v165
	s_nop 0
	v_cndmask_b32_e32 v204, v162, v164, vcc
	v_lshl_add_u64 v[162:163], s[0:1], 0, v[44:45]
	flat_load_dword v176, v[162:163]
	v_not_b32_e32 v164, v168
	v_or_b32_e32 v162, 0x80000000, v168
	v_cmp_gt_i32_e32 vcc, 0, v168
	s_nop 1
	v_cndmask_b32_e32 v203, v162, v164, vcc
	v_lshl_add_u64 v[162:163], s[0:1], 0, v[42:43]
	v_not_b32_e32 v164, v179
	flat_load_dword v168, v[162:163]
	v_or_b32_e32 v162, 0x80000000, v179
	v_cmp_gt_i32_e32 vcc, 0, v179
	s_nop 1
	v_cndmask_b32_e32 v202, v162, v164, vcc
	v_lshl_add_u64 v[162:163], s[0:1], 0, v[40:41]
	s_add_u32 s0, s12, 0x5000
	s_addc_u32 s1, s13, 0
	v_not_b32_e32 v164, v165
	flat_load_dword v178, v[162:163]
	v_cmp_gt_i32_e32 vcc, 0, v165
	v_lshl_add_u64 v[162:163], s[0:1], 0, v[0:1]
	flat_load_dword v165, v[162:163]
	v_cndmask_b32_e32 v201, v177, v164, vcc
	v_not_b32_e32 v164, v166
	v_or_b32_e32 v162, 0x80000000, v166
	v_cmp_gt_i32_e32 vcc, 0, v166
	v_or_b32_e32 v163, 0x80000000, v180
	v_or_b32_e32 v177, 0x80000000, v167
	v_cndmask_b32_e32 v200, v162, v164, vcc
	v_not_b32_e32 v162, v180
	v_cmp_gt_i32_e32 vcc, 0, v180
	v_not_b32_e32 v164, v167
	s_nop 0
	v_cndmask_b32_e32 v199, v163, v162, vcc
	v_lshl_add_u64 v[162:163], s[0:1], 0, v[38:39]
	flat_load_dword v166, v[162:163]
	v_lshl_add_u64 v[162:163], s[0:1], 0, v[36:37]
	flat_load_dword v179, v[162:163]
	v_cmp_gt_i32_e32 vcc, 0, v167
	v_lshl_add_u64 v[162:163], s[0:1], 0, v[34:35]
	v_or_b32_e32 v167, 0x80000000, v170
	v_cndmask_b32_e32 v198, v177, v164, vcc
	v_not_b32_e32 v164, v170
	flat_load_dword v177, v[162:163]
	v_cmp_gt_i32_e32 vcc, 0, v170
	v_lshl_add_u64 v[162:163], s[0:1], 0, v[62:63]
	flat_load_dword v170, v[162:163]
	v_cndmask_b32_e32 v197, v167, v164, vcc
	v_not_b32_e32 v164, v171
	v_or_b32_e32 v167, 0x80000000, v171
	v_cmp_gt_i32_e32 vcc, 0, v171
	v_lshl_add_u64 v[162:163], s[0:1], 0, v[60:61]
	s_nop 0
	v_cndmask_b32_e32 v196, v167, v164, vcc
	v_not_b32_e32 v164, v172
	flat_load_dword v167, v[162:163]
	v_or_b32_e32 v162, 0x80000000, v172
	v_cmp_gt_i32_e32 vcc, 0, v172
	s_nop 1
	v_cndmask_b32_e32 v195, v162, v164, vcc
	v_lshl_add_u64 v[162:163], s[0:1], 0, v[58:59]
	v_not_b32_e32 v164, v173
	flat_load_dword v171, v[162:163]
	v_or_b32_e32 v162, 0x80000000, v173
	v_cmp_gt_i32_e32 vcc, 0, v173
	v_or_b32_e32 v173, 0x80000000, v174
	s_nop 0
	v_cndmask_b32_e32 v194, v162, v164, vcc
	v_lshl_add_u64 v[162:163], s[0:1], 0, v[56:57]
	flat_load_dword v172, v[162:163]
	v_lshl_add_u64 v[162:163], s[0:1], 0, v[52:53]
	flat_load_dword v142, v[162:163]
	v_not_b32_e32 v164, v174
	v_cmp_gt_i32_e32 vcc, 0, v174
	v_lshl_add_u64 v[162:163], s[0:1], 0, v[54:55]
	flat_load_dword v174, v[162:163]
	v_cndmask_b32_e32 v193, v173, v164, vcc
	s_waitcnt vmcnt(0) lgkmcnt(0)
; DI unsigned f2key(float f) { const unsigned u = __float_as_uint(f); return (u & 0x80000000u) ? ~u : (u | 0x80000000u); }
; template <int NV>
; DI void topk_row(const float* row, int s, LAS int* lst, int lane) {
;     ...
;     for (int jo = 0; jo < NV / 16; ++jo) { const float* rb = row + jo * 1024;
; #pragma unroll
;         for (int ji = 0; ji < 16; ++ji) { const int j = jo * 16 + ji; const unsigned u = f2key(rb[ji * 64 + lane]); key[j] = (j * 64 + lane <= s) ? u : 0u; } }
	v_not_b32_e32 v164, v169
	v_or_b32_e32 v173, 0x80000000, v169
	v_cmp_gt_i32_e32 vcc, 0, v169
	v_lshl_add_u64 v[162:163], s[0:1], 0, v[50:51]
	v_or_b32_e32 v169, 0x80000000, v175
	v_cndmask_b32_e32 v192, v173, v164, vcc
	v_not_b32_e32 v164, v175
	flat_load_dword v173, v[162:163]
	v_cmp_gt_i32_e32 vcc, 0, v175
	v_lshl_add_u64 v[162:163], s[0:1], 0, v[48:49]
	s_nop 0
	v_cndmask_b32_e32 v191, v169, v164, vcc
	v_not_b32_e32 v164, v176
	flat_load_dword v169, v[162:163]
	v_or_b32_e32 v162, 0x80000000, v176
	v_cmp_gt_i32_e32 vcc, 0, v176
	v_or_b32_e32 v176, 0x80000000, v168
	s_nop 0
	v_cndmask_b32_e32 v190, v162, v164, vcc
	v_lshl_add_u64 v[162:163], s[0:1], 0, v[46:47]
	flat_load_dword v175, v[162:163]
	v_lshl_add_u64 v[162:163], s[0:1], 0, v[44:45]
	flat_load_dword v143, v[162:163]
	v_lshl_add_u64 v[162:163], s[0:1], 0, v[42:43]
	flat_load_dword v144, v[162:163]
	v_lshl_add_u64 v[162:163], s[0:1], 0, v[40:41]
	flat_load_dword v145, v[162:163]
	s_add_u32 s0, s12, 0x6000
	v_not_b32_e32 v164, v168
	v_cmp_gt_i32_e32 vcc, 0, v168
	s_addc_u32 s1, s13, 0
	v_or_b32_e32 v168, 0x80000000, v178
	v_cndmask_b32_e32 v189, v176, v164, vcc
	v_not_b32_e32 v164, v178
	v_cmp_gt_i32_e32 vcc, 0, v178
	v_lshl_add_u64 v[162:163], s[0:1], 0, v[0:1]
	flat_load_dword v146, v[162:163]
	v_cndmask_b32_e32 v187, v168, v164, vcc
	v_not_b32_e32 v164, v165
	v_or_b32_e32 v168, 0x80000000, v165
	v_cmp_gt_i32_e32 vcc, 0, v165
	v_not_b32_e32 v162, v166
	v_or_b32_e32 v163, 0x80000000, v166
	v_cndmask_b32_e32 v188, v168, v164, vcc
	v_cmp_gt_i32_e32 vcc, 0, v166
	v_not_b32_e32 v164, v179
	v_or_b32_e32 v166, 0x80000000, v177
	v_cndmask_b32_e32 v186, v163, v162, vcc
	v_lshl_add_u64 v[162:163], s[0:1], 0, v[38:39]
	flat_load_dword v165, v[162:163]
	v_or_b32_e32 v162, 0x80000000, v179
	v_cmp_gt_i32_e32 vcc, 0, v179
	s_nop 1
	v_cndmask_b32_e32 v185, v162, v164, vcc
	v_not_b32_e32 v164, v177
	v_lshl_add_u64 v[162:163], s[0:1], 0, v[36:37]
	v_cmp_gt_i32_e32 vcc, 0, v177
	flat_load_dword v168, v[162:163]
	v_not_b32_e32 v162, v170
	v_cndmask_b32_e32 v184, v166, v164, vcc
	v_or_b32_e32 v163, 0x80000000, v170
	v_cmp_gt_i32_e32 vcc, 0, v170
	v_not_b32_e32 v164, v167
	s_nop 0
	v_cndmask_b32_e32 v183, v163, v162, vcc
	v_lshl_add_u64 v[162:163], s[0:1], 0, v[34:35]
	flat_load_dword v166, v[162:163]
	v_or_b32_e32 v162, 0x80000000, v167
	v_cmp_gt_i32_e32 vcc, 0, v167
	v_or_b32_e32 v167, 0x80000000, v171
	s_nop 0
	v_cndmask_b32_e32 v182, v162, v164, vcc
	v_not_b32_e32 v164, v171
	v_lshl_add_u64 v[162:163], s[0:1], 0, v[62:63]
	v_cmp_gt_i32_e32 vcc, 0, v171
	flat_load_dword v147, v[162:163]
	v_not_b32_e32 v162, v172
	v_cndmask_b32_e32 v181, v167, v164, vcc
	v_or_b32_e32 v163, 0x80000000, v172
	v_cmp_gt_i32_e32 vcc, 0, v172
	v_not_b32_e32 v164, v142
	s_nop 0
	v_cndmask_b32_e32 v180, v163, v162, vcc
	v_lshl_add_u64 v[162:163], s[0:1], 0, v[60:61]
	flat_load_dword v167, v[162:163]
	v_or_b32_e32 v162, 0x80000000, v142
	v_cmp_gt_i32_e32 vcc, 0, v142
	v_not_b32_e32 v142, v174
	s_nop 0
	v_cndmask_b32_e32 v179, v162, v164, vcc
	v_lshl_add_u64 v[162:163], s[0:1], 0, v[58:59]
	flat_load_dword v148, v[162:163]
	v_or_b32_e32 v164, 0x80000000, v174
	v_cmp_gt_i32_e32 vcc, 0, v174
	s_waitcnt vmcnt(0) lgkmcnt(0)
	v_or_b32_e32 v162, 0x80000000, v173
	v_cndmask_b32_e32 v178, v164, v142, vcc
	v_not_b32_e32 v142, v173
	v_cmp_gt_i32_e32 vcc, 0, v173
	v_or_b32_e32 v164, 0x80000000, v169
	s_nop 0
	v_cndmask_b32_e32 v177, v162, v142, vcc
	v_not_b32_e32 v142, v169
	v_lshl_add_u64 v[162:163], s[0:1], 0, v[56:57]
	v_cmp_gt_i32_e32 vcc, 0, v169
	flat_load_dword v149, v[162:163]
	v_or_b32_e32 v162, 0x80000000, v175
	v_cndmask_b32_e32 v176, v164, v142, vcc
	v_not_b32_e32 v142, v175
	v_cmp_gt_i32_e32 vcc, 0, v175
	s_nop 1
	v_cndmask_b32_e32 v175, v162, v142, vcc
	v_lshl_add_u64 v[162:163], s[0:1], 0, v[52:53]
	v_not_b32_e32 v142, v143
	flat_load_dword v150, v[162:163]
	v_or_b32_e32 v162, 0x80000000, v143
	v_cmp_gt_i32_e32 vcc, 0, v143
	s_nop 1
	v_cndmask_b32_e32 v174, v162, v142, vcc
	v_lshl_add_u64 v[162:163], s[0:1], 0, v[54:55]
	v_not_b32_e32 v142, v144
	flat_load_dword v143, v[162:163]
	v_or_b32_e32 v162, 0x80000000, v144
	v_cmp_gt_i32_e32 vcc, 0, v144
	v_or_b32_e32 v144, 0x80000000, v145
	s_nop 0
	v_cndmask_b32_e32 v173, v162, v142, vcc
	v_not_b32_e32 v142, v145
	v_cmp_gt_i32_e32 vcc, 0, v145
	v_lshl_add_u64 v[162:163], s[0:1], 0, v[50:51]
	v_or_b32_e32 v145, 0x80000000, v146
	v_cndmask_b32_e32 v172, v144, v142, vcc
	flat_load_dword v144, v[162:163]
	v_not_b32_e32 v142, v146
	v_cmp_gt_i32_e32 vcc, 0, v146
	v_lshl_add_u64 v[162:163], s[0:1], 0, v[48:49]
	v_or_b32_e32 v146, 0x80000000, v165
	v_cndmask_b32_e32 v142, v145, v142, vcc
	flat_load_dword v145, v[162:163]
	v_cmp_lt_u32_e32 vcc, s2, v161
	s_movk_i32 s2, 0x183f
	v_lshl_add_u64 v[162:163], s[0:1], 0, v[46:47]
	v_cndmask_b32_e32 v171, 0, v142, vcc
	v_not_b32_e32 v142, v165
	v_cmp_gt_i32_e32 vcc, 0, v165
	flat_load_dword v151, v[162:163]
	v_lshl_add_u64 v[162:163], s[0:1], 0, v[44:45]
	v_cndmask_b32_e32 v142, v146, v142, vcc
	v_cmp_lt_u32_e32 vcc, s2, v161
	v_or_b32_e32 v146, 0x80000000, v168
	s_movk_i32 s2, 0x187f
	v_cndmask_b32_e32 v170, 0, v142, vcc
	v_not_b32_e32 v142, v168
	v_cmp_gt_i32_e32 vcc, 0, v168
	flat_load_dword v152, v[162:163]
	v_lshl_add_u64 v[162:163], s[0:1], 0, v[42:43]
	v_cndmask_b32_e32 v142, v146, v142, vcc
	v_cmp_lt_u32_e32 vcc, s2, v161
	v_or_b32_e32 v146, 0x80000000, v166
	s_movk_i32 s2, 0x18bf
	v_cndmask_b32_e32 v169, 0, v142, vcc
	v_not_b32_e32 v142, v166
	v_cmp_gt_i32_e32 vcc, 0, v166
	s_nop 1
	v_cndmask_b32_e32 v142, v146, v142, vcc
	v_cmp_lt_u32_e32 vcc, s2, v161
	v_or_b32_e32 v146, 0x80000000, v147
	s_movk_i32 s2, 0x18ff
	v_cndmask_b32_e32 v168, 0, v142, vcc
	v_not_b32_e32 v142, v147
	v_cmp_gt_i32_e32 vcc, 0, v147
	v_or_b32_e32 v147, 0x80000000, v167
	s_nop 0
	v_cndmask_b32_e32 v142, v146, v142, vcc
	flat_load_dword v146, v[162:163]
	v_cmp_lt_u32_e32 vcc, s2, v161
	v_lshl_add_u64 v[162:163], s[0:1], 0, v[40:41]
	s_movk_i32 s0, 0x193f
	v_cndmask_b32_e32 v166, 0, v142, vcc
	v_not_b32_e32 v142, v167
	v_cmp_gt_i32_e32 vcc, 0, v167
	s_movk_i32 s2, 0x197f
	s_nop 0
	v_cndmask_b32_e32 v142, v147, v142, vcc
	v_cmp_lt_u32_e32 vcc, s0, v161
	s_add_u32 s0, s12, 0x7000
	flat_load_dword v147, v[162:163]
	s_addc_u32 s1, s13, 0
	v_lshl_add_u64 v[38:39], s[0:1], 0, v[38:39]
	v_cndmask_b32_e32 v164, 0, v142, vcc
	v_not_b32_e32 v142, v148
	v_cmp_gt_i32_e32 vcc, 0, v148
	flat_load_dword v38, v[38:39]
	v_or_b32_e32 v162, 0x80000000, v148
	v_cndmask_b32_e32 v142, v162, v142, vcc
	v_lshl_add_u64 v[162:163], s[0:1], 0, v[0:1]
	flat_load_dword v0, v[162:163]
	v_cmp_lt_u32_e32 vcc, s2, v161
	s_waitcnt vmcnt(0) lgkmcnt(0)
; DI unsigned f2key(float f) { const unsigned u = __float_as_uint(f); return (u & 0x80000000u) ? ~u : (u | 0x80000000u); }
; template <int NV>
; DI void topk_row(const float* row, int s, LAS int* lst, int lane) {
;     ...
;     for (int jo = 0; jo < NV / 16; ++jo) { const float* rb = row + jo * 1024;
; #pragma unroll
;         for (int ji = 0; ji < 16; ++ji) { const int j = jo * 16 + ji; const unsigned u = f2key(rb[ji * 64 + lane]); key[j] = (j * 64 + lane <= s) ? u : 0u; } }
	v_or_b32_e32 v148, 0x80000000, v149
	s_movk_i32 s2, 0x19bf
	v_cndmask_b32_e32 v167, 0, v142, vcc
	v_not_b32_e32 v142, v149
	v_cmp_gt_i32_e32 vcc, 0, v149
	v_lshl_add_u64 v[36:37], s[0:1], 0, v[36:37]
	flat_load_dword v36, v[36:37]
	v_cndmask_b32_e32 v142, v148, v142, vcc
	v_cmp_lt_u32_e32 vcc, s2, v161
	v_not_b32_e32 v39, v150
	s_movk_i32 s2, 0x19ff
	v_cndmask_b32_e32 v165, 0, v142, vcc
	v_or_b32_e32 v142, 0x80000000, v150
	v_cmp_gt_i32_e32 vcc, 0, v150
	v_or_b32_e32 v37, 0x80000000, v143
	v_lshl_add_u64 v[34:35], s[0:1], 0, v[34:35]
	v_cndmask_b32_e32 v39, v142, v39, vcc
	v_cmp_lt_u32_e32 vcc, s2, v161
	s_movk_i32 s2, 0x1a3f
	v_or_b32_e32 v142, 0x80000000, v144
	v_cndmask_b32_e32 v162, 0, v39, vcc
	v_not_b32_e32 v39, v143
	v_cmp_gt_i32_e32 vcc, 0, v143
	s_nop 1
	v_cndmask_b32_e32 v37, v37, v39, vcc
	flat_load_dword v39, v[34:35]
	v_cmp_lt_u32_e32 vcc, s2, v161
	v_lshl_add_u64 v[34:35], s[0:1], 0, v[62:63]
	s_movk_i32 s2, 0x1a7f
	v_cndmask_b32_e32 v163, 0, v37, vcc
	v_not_b32_e32 v37, v144
	v_cmp_gt_i32_e32 vcc, 0, v144
	flat_load_dword v63, v[34:35]
	s_nop 0
	v_cndmask_b32_e32 v34, v142, v37, vcc
	v_cmp_lt_u32_e32 vcc, s2, v161
	v_not_b32_e32 v37, v145
	s_movk_i32 s2, 0x1abf
	v_cndmask_b32_e32 v62, 0, v34, vcc
	v_lshl_add_u64 v[34:35], s[0:1], 0, v[60:61]
	flat_load_dword v60, v[34:35]
	v_or_b32_e32 v34, 0x80000000, v145
	v_cmp_gt_i32_e32 vcc, 0, v145
	v_or_b32_e32 v61, 0x80000000, v151
	s_nop 0
	v_cndmask_b32_e32 v37, v34, v37, vcc
	v_lshl_add_u64 v[34:35], s[0:1], 0, v[58:59]
	flat_load_dword v59, v[34:35]
	v_cmp_lt_u32_e32 vcc, s2, v161
	v_lshl_add_u64 v[34:35], s[0:1], 0, v[56:57]
	s_movk_i32 s2, 0x1aff
	v_cndmask_b32_e32 v58, 0, v37, vcc
	v_not_b32_e32 v37, v151
	v_cmp_gt_i32_e32 vcc, 0, v151
	flat_load_dword v57, v[34:35]
	s_nop 0
	v_cndmask_b32_e32 v34, v61, v37, vcc
	v_cmp_lt_u32_e32 vcc, s2, v161
	v_not_b32_e32 v37, v152
	s_movk_i32 s2, 0x1b3f
	v_cndmask_b32_e32 v56, 0, v34, vcc
	v_lshl_add_u64 v[34:35], s[0:1], 0, v[52:53]
	flat_load_dword v53, v[34:35]
	v_or_b32_e32 v34, 0x80000000, v152
	v_cmp_gt_i32_e32 vcc, 0, v152
	s_nop 1
	v_cndmask_b32_e32 v37, v34, v37, vcc
	v_lshl_add_u64 v[34:35], s[0:1], 0, v[54:55]
	flat_load_dword v54, v[34:35]
	v_cmp_lt_u32_e32 vcc, s2, v161
	v_or_b32_e32 v55, 0x80000000, v146
	v_lshl_add_u64 v[34:35], s[0:1], 0, v[50:51]
	v_cndmask_b32_e32 v52, 0, v37, vcc
	v_not_b32_e32 v37, v146
	v_cmp_gt_i32_e32 vcc, 0, v146
	s_movk_i32 s2, 0x1b7f
	flat_load_dword v61, v[34:35]
	v_cndmask_b32_e32 v34, v55, v37, vcc
	v_cmp_lt_u32_e32 vcc, s2, v161
	v_not_b32_e32 v37, v147
	s_movk_i32 s2, 0x1bbf
	v_cndmask_b32_e32 v50, 0, v34, vcc
	v_lshl_add_u64 v[34:35], s[0:1], 0, v[48:49]
	flat_load_dword v55, v[34:35]
	v_or_b32_e32 v34, 0x80000000, v147
	v_cmp_gt_i32_e32 vcc, 0, v147
	s_nop 1
	v_cndmask_b32_e32 v37, v34, v37, vcc
	v_lshl_add_u64 v[34:35], s[0:1], 0, v[46:47]
	flat_load_dword v142, v[34:35]
	v_cmp_lt_u32_e32 vcc, s2, v161
	v_lshl_add_u64 v[34:35], s[0:1], 0, v[44:45]
	v_or_b32_e32 v46, 0x80000000, v0
	v_cndmask_b32_e32 v49, 0, v37, vcc
	v_not_b32_e32 v37, v0
	flat_load_dword v143, v[34:35]
	v_cmp_gt_i32_e32 vcc, 0, v0
	s_movk_i32 s2, 0x1bff
	v_lshl_add_u64 v[34:35], s[0:1], 0, v[42:43]
	v_cndmask_b32_e32 v0, v46, v37, vcc
	v_cmp_lt_u32_e32 vcc, s2, v161
	flat_load_dword v144, v[34:35]
	v_or_b32_e32 v34, 0x80000000, v38
	v_cndmask_b32_e32 v48, 0, v0, vcc
	v_not_b32_e32 v0, v38
	v_cmp_gt_i32_e32 vcc, 0, v38
	s_nop 1
	v_cndmask_b32_e32 v0, v34, v0, vcc
	v_lshl_add_u64 v[34:35], s[0:1], 0, v[40:41]
	flat_load_dword v34, v[34:35]
	s_movk_i32 s0, 0x1c3f
	v_cmp_lt_u32_e32 vcc, s0, v161
	s_waitcnt vmcnt(0) lgkmcnt(0)
	v_or_b32_e32 v35, 0x80000000, v36
	s_movk_i32 s0, 0x1c7f
	v_cndmask_b32_e32 v51, 0, v0, vcc
	v_not_b32_e32 v0, v36
	v_cmp_gt_i32_e32 vcc, 0, v36
	s_nop 1
	v_cndmask_b32_e32 v0, v35, v0, vcc
	v_cmp_lt_u32_e32 vcc, s0, v161
	v_or_b32_e32 v35, 0x80000000, v39
	s_movk_i32 s0, 0x1cbf
	v_cndmask_b32_e32 v47, 0, v0, vcc
	v_not_b32_e32 v0, v39
	v_cmp_gt_i32_e32 vcc, 0, v39
	s_nop 1
	v_cndmask_b32_e32 v0, v35, v0, vcc
	v_cmp_lt_u32_e32 vcc, s0, v161
	v_or_b32_e32 v35, 0x80000000, v63
	s_movk_i32 s0, 0x1cff
	v_cndmask_b32_e32 v46, 0, v0, vcc
	v_not_b32_e32 v0, v63
	v_cmp_gt_i32_e32 vcc, 0, v63
	s_nop 1
	v_cndmask_b32_e32 v0, v35, v0, vcc
	v_cmp_lt_u32_e32 vcc, s0, v161
	v_or_b32_e32 v35, 0x80000000, v60
	s_movk_i32 s0, 0x1d3f
	v_cndmask_b32_e32 v45, 0, v0, vcc
	v_not_b32_e32 v0, v60
	v_cmp_gt_i32_e32 vcc, 0, v60
	s_nop 1
	v_cndmask_b32_e32 v0, v35, v0, vcc
	v_cmp_lt_u32_e32 vcc, s0, v161
	v_or_b32_e32 v35, 0x80000000, v59
	s_movk_i32 s0, 0x1d7f
	v_cndmask_b32_e32 v44, 0, v0, vcc
	v_not_b32_e32 v0, v59
	v_cmp_gt_i32_e32 vcc, 0, v59
	s_nop 1
	v_cndmask_b32_e32 v0, v35, v0, vcc
	v_cmp_lt_u32_e32 vcc, s0, v161
	v_or_b32_e32 v35, 0x80000000, v57
	s_movk_i32 s0, 0x1dbf
	v_cndmask_b32_e32 v43, 0, v0, vcc
	v_not_b32_e32 v0, v57
	v_cmp_gt_i32_e32 vcc, 0, v57
	s_nop 1
	v_cndmask_b32_e32 v0, v35, v0, vcc
	v_cmp_lt_u32_e32 vcc, s0, v161
	v_or_b32_e32 v35, 0x80000000, v53
	s_movk_i32 s0, 0x1dff
	v_cndmask_b32_e32 v42, 0, v0, vcc
	v_not_b32_e32 v0, v53
	v_cmp_gt_i32_e32 vcc, 0, v53
	v_or_b32_e32 v53, 0x80000000, v34
	s_nop 0
	v_cndmask_b32_e32 v0, v35, v0, vcc
	v_cmp_lt_u32_e32 vcc, s0, v161
	v_or_b32_e32 v35, 0x80000000, v54
	s_movk_i32 s0, 0x1e3f
	v_cndmask_b32_e32 v41, 0, v0, vcc
	v_not_b32_e32 v0, v54
	v_cmp_gt_i32_e32 vcc, 0, v54
	s_nop 1
	v_cndmask_b32_e32 v0, v35, v0, vcc
	v_cmp_lt_u32_e32 vcc, s0, v161
	v_or_b32_e32 v35, 0x80000000, v61
	s_movk_i32 s0, 0x1e7f
	v_cndmask_b32_e32 v40, 0, v0, vcc
	v_not_b32_e32 v0, v61
	v_cmp_gt_i32_e32 vcc, 0, v61
	s_nop 1
	v_cndmask_b32_e32 v0, v35, v0, vcc
	v_cmp_lt_u32_e32 vcc, s0, v161
; DI unsigned f2key(float f) { const unsigned u = __float_as_uint(f); return (u & 0x80000000u) ? ~u : (u | 0x80000000u); }
; template <int NV>
; DI void topk_row(const float* row, int s, LAS int* lst, int lane) {
;     ...
;     for (int jo = 0; jo < NV / 16; ++jo) { const float* rb = row + jo * 1024;
; #pragma unroll
;         for (int ji = 0; ji < 16; ++ji) { const int j = jo * 16 + ji; const unsigned u = f2key(rb[ji * 64 + lane]); key[j] = (j * 64 + lane <= s) ? u : 0u; } }
;     unsigned T = 0u;
; #pragma unroll 1
	v_or_b32_e32 v35, 0x80000000, v55
	s_movk_i32 s0, 0x1ebf
	v_cndmask_b32_e32 v39, 0, v0, vcc
	v_not_b32_e32 v0, v55
	v_cmp_gt_i32_e32 vcc, 0, v55
	s_nop 1
	v_cndmask_b32_e32 v0, v35, v0, vcc
	v_cmp_lt_u32_e32 vcc, s0, v161
	v_or_b32_e32 v35, 0x80000000, v142
	s_movk_i32 s0, 0x1eff
	v_cndmask_b32_e32 v38, 0, v0, vcc
	v_not_b32_e32 v0, v142
	v_cmp_gt_i32_e32 vcc, 0, v142
	s_nop 1
	v_cndmask_b32_e32 v0, v35, v0, vcc
	v_cmp_lt_u32_e32 vcc, s0, v161
	v_or_b32_e32 v35, 0x80000000, v143
	s_movk_i32 s0, 0x1f3f
	v_cndmask_b32_e32 v37, 0, v0, vcc
	v_not_b32_e32 v0, v143
	v_cmp_gt_i32_e32 vcc, 0, v143
	s_nop 1
	v_cndmask_b32_e32 v0, v35, v0, vcc
	v_cmp_lt_u32_e32 vcc, s0, v161
	v_or_b32_e32 v35, 0x80000000, v144
	s_movk_i32 s0, 0x1f7f
	v_cndmask_b32_e32 v36, 0, v0, vcc
	v_not_b32_e32 v0, v144
	v_cmp_gt_i32_e32 vcc, 0, v144
	s_nop 1
	v_cndmask_b32_e32 v0, v35, v0, vcc
	v_cmp_lt_u32_e32 vcc, s0, v161
	s_movk_i32 s0, 0x1fbf
	s_nop 0
	v_cndmask_b32_e32 v35, 0, v0, vcc
	v_not_b32_e32 v0, v34
	v_cmp_gt_i32_e32 vcc, 0, v34
	v_mov_b32_e32 v34, 0
	s_nop 0
	v_cndmask_b32_e32 v0, v53, v0, vcc
	v_cmp_lt_u32_e32 vcc, s0, v161
	v_mov_b32_e32 v53, 31
	s_nop 0
	v_cndmask_b32_e32 v0, 0, v0, vcc
	v_max_u32_e32 v54, v141, v137
	v_max_u32_e32 v55, v140, v136
	v_max_u32_e32 v34, v139, v135
	v_max_u32_e32 v53, v138, v134
	v_max_u32_e32 v54, v54, v133
	v_max_u32_e32 v55, v55, v132
	v_max_u32_e32 v34, v34, v251
	v_max_u32_e32 v53, v53, v248
	v_max_u32_e32 v54, v54, v247
	v_max_u32_e32 v55, v55, v253
	v_max_u32_e32 v34, v34, v249
	v_max_u32_e32 v53, v53, v252
	v_max_u32_e32 v54, v54, v128
	v_max_u32_e32 v55, v55, v130
	v_max_u32_e32 v34, v34, v131
	v_max_u32_e32 v53, v53, v129
	v_max_u32_e32 v54, v54, v250
	v_max_u32_e32 v55, v55, v246
	v_max_u32_e32 v34, v34, v245
	v_max_u32_e32 v53, v53, v244
	v_max_u32_e32 v54, v54, v243
	v_max_u32_e32 v55, v55, v242
	v_max_u32_e32 v34, v34, v241
	v_max_u32_e32 v53, v53, v240
	v_max_u32_e32 v54, v54, v239
	v_max_u32_e32 v55, v55, v238
	v_max_u32_e32 v34, v34, v237
	v_max_u32_e32 v53, v53, v236
	v_max_u32_e32 v54, v54, v235
	v_max_u32_e32 v55, v55, v234
	v_max_u32_e32 v34, v34, v233
	v_max_u32_e32 v53, v53, v232
	v_max_u32_e32 v54, v54, v231
	v_max_u32_e32 v55, v55, v230
	v_max_u32_e32 v34, v34, v229
	v_max_u32_e32 v53, v53, v228
	v_max_u32_e32 v54, v54, v227
	v_max_u32_e32 v55, v55, v226
	v_max_u32_e32 v34, v34, v225
	v_max_u32_e32 v53, v53, v224
	v_max_u32_e32 v54, v54, v223
	v_max_u32_e32 v55, v55, v222
	v_max_u32_e32 v34, v34, v221
	v_max_u32_e32 v53, v53, v220
	v_max_u32_e32 v54, v54, v219
	v_max_u32_e32 v55, v55, v218
	v_max_u32_e32 v34, v34, v217
	v_max_u32_e32 v53, v53, v216
	v_max_u32_e32 v54, v54, v215
	v_max_u32_e32 v55, v55, v214
	v_max_u32_e32 v34, v34, v213
	v_max_u32_e32 v53, v53, v212
	v_max_u32_e32 v54, v54, v211
	v_max_u32_e32 v55, v55, v210
	v_max_u32_e32 v34, v34, v209
	v_max_u32_e32 v53, v53, v208
	v_max_u32_e32 v54, v54, v207
	v_max_u32_e32 v55, v55, v206
	v_max_u32_e32 v34, v34, v205
	v_max_u32_e32 v53, v53, v204
	v_max_u32_e32 v54, v54, v203
	v_max_u32_e32 v55, v55, v202
	v_max_u32_e32 v34, v34, v201
	v_max_u32_e32 v53, v53, v200
	v_max_u32_e32 v54, v54, v199
	v_max_u32_e32 v55, v55, v198
	v_max_u32_e32 v34, v34, v197
	v_max_u32_e32 v53, v53, v196
	v_max_u32_e32 v54, v54, v195
	v_max_u32_e32 v55, v55, v194
	v_max_u32_e32 v34, v34, v193
	v_max_u32_e32 v53, v53, v192
	v_max_u32_e32 v54, v54, v191
	v_max_u32_e32 v55, v55, v190
	v_max_u32_e32 v34, v34, v189
	v_max_u32_e32 v53, v53, v187
	v_max_u32_e32 v54, v54, v188
	v_max_u32_e32 v55, v55, v186
	v_max_u32_e32 v34, v34, v185
	v_max_u32_e32 v53, v53, v184
	v_max_u32_e32 v54, v54, v183
	v_max_u32_e32 v55, v55, v182
	v_max_u32_e32 v34, v34, v181
	v_max_u32_e32 v53, v53, v180
	v_max_u32_e32 v54, v54, v179
	v_max_u32_e32 v55, v55, v178
	v_max_u32_e32 v34, v34, v177
	v_max_u32_e32 v53, v53, v176
	v_max_u32_e32 v54, v54, v175
	v_max_u32_e32 v55, v55, v174
	v_max_u32_e32 v34, v34, v173
	v_max_u32_e32 v53, v53, v172
	v_max_u32_e32 v54, v54, v171
	v_max_u32_e32 v55, v55, v170
	v_max_u32_e32 v34, v34, v169
	v_max_u32_e32 v53, v53, v168
	v_max_u32_e32 v54, v54, v166
	v_max_u32_e32 v55, v55, v164
	v_max_u32_e32 v34, v34, v167
	v_max_u32_e32 v53, v53, v165
	v_max_u32_e32 v54, v54, v162
	v_max_u32_e32 v55, v55, v163
	v_max_u32_e32 v34, v34, v62
	v_max_u32_e32 v53, v53, v58
	v_max_u32_e32 v54, v54, v56
	v_max_u32_e32 v55, v55, v52
	v_max_u32_e32 v34, v34, v50
	v_max_u32_e32 v53, v53, v49
	v_max_u32_e32 v54, v54, v48
	v_max_u32_e32 v55, v55, v51
	v_max_u32_e32 v34, v34, v47
	v_max_u32_e32 v53, v53, v46
	v_max_u32_e32 v54, v54, v45
	v_max_u32_e32 v55, v55, v44
	v_max_u32_e32 v34, v34, v43
	v_max_u32_e32 v53, v53, v42
	v_max_u32_e32 v54, v54, v41
	v_max_u32_e32 v55, v55, v40
	v_max_u32_e32 v34, v34, v39
	v_max_u32_e32 v53, v53, v38
	v_max_u32_e32 v54, v54, v37
	v_max_u32_e32 v55, v55, v36
	v_max_u32_e32 v34, v34, v35
	v_max_u32_e32 v53, v53, v0
	v_max3_u32 v255, v54, v55, v34
	v_min3_u32 v54, v54, v55, v34
	v_max_u32_e32 v255, v255, v53
	v_min_u32_e32 v54, v54, v53
	s_nop 1
	v_max_u32_dpp v255, v255, v255 quad_perm:[1,0,3,2] row_mask:0xf bank_mask:0xf bound_ctrl:1
	v_min_u32_dpp v54, v54, v54 quad_perm:[1,0,3,2] row_mask:0xf bank_mask:0xf bound_ctrl:1
	s_nop 1
	v_max_u32_dpp v255, v255, v255 quad_perm:[2,3,0,1] row_mask:0xf bank_mask:0xf bound_ctrl:1
	v_min_u32_dpp v54, v54, v54 quad_perm:[2,3,0,1] row_mask:0xf bank_mask:0xf bound_ctrl:1
	s_nop 1
	v_max_u32_dpp v255, v255, v255 row_half_mirror row_mask:0xf bank_mask:0xf bound_ctrl:1
	v_min_u32_dpp v54, v54, v54 row_half_mirror row_mask:0xf bank_mask:0xf bound_ctrl:1
	s_nop 1
	v_max_u32_dpp v255, v255, v255 row_mirror row_mask:0xf bank_mask:0xf bound_ctrl:1
	v_min_u32_dpp v54, v54, v54 row_mirror row_mask:0xf bank_mask:0xf bound_ctrl:1
	s_nop 1
	v_readlane_b32 s0, v255, 0
	v_readlane_b32 s1, v255, 16
	s_max_u32 s0, s0, s1
	v_readlane_b32 s1, v255, 32
	s_max_u32 s0, s0, s1
	v_readlane_b32 s1, v255, 48
	s_max_u32 s100, s0, s1
	v_readlane_b32 s0, v54, 0
	v_readlane_b32 s1, v54, 16
	s_min_u32 s0, s0, s1
	v_readlane_b32 s1, v54, 32
	s_min_u32 s0, s0, s1
	v_readlane_b32 s1, v54, 48
	s_min_u32 s101, s0, s1
	s_xor_b32 s0, s100, s101
	s_max_u32 s0, s0, 1
	s_flbit_i32_b32 s1, s0
	s_sub_u32 s1, 31, s1
	s_lshl_b32 s0, 1, s1
	s_lshl_b32 s0, s0, 1
	s_sub_u32 s0, s0, 1
	s_andn2_b32 s0, s100, s0
	v_mov_b32_e32 v34, s0
	v_mov_b32_e32 v53, s1

; DI unsigned f2key(float f) { const unsigned u = __float_as_uint(f); return (u & 0x80000000u) ? ~u : (u | 0x80000000u); }
; template <int NV>
; DI void topk_row(const float* row, int s, LAS int* lst, int lane) {
;     ...
;     for (int jo = 0; jo < NV / 16; ++jo) { const float* rb = row + jo * 1024;
; #pragma unroll
;         for (int ji = 0; ji < 16; ++ji) { const int j = jo * 16 + ji; const unsigned u = f2key(rb[ji * 64 + lane]); key[j] = (j * 64 + lane <= s) ? u : 0u; } }
.LBB0_2483:
	s_mov_b64 s[0:1], 0
	v_mov_b32_e32 v34, v159
	s_cbranch_execz .LBB0_2869
	v_lshlrev_b32_e32 v0, 2, v2
	v_lshl_add_u64 v[40:41], s[12:13], 0, v[0:1]
	flat_load_dword v48, v[40:41]
	flat_load_dword v49, v[40:41] offset:256
	flat_load_dword v50, v[40:41] offset:512
	flat_load_dword v51, v[40:41] offset:768
	flat_load_dword v52, v[40:41] offset:1024
	flat_load_dword v53, v[40:41] offset:1280
	flat_load_dword v54, v[40:41] offset:1536
	flat_load_dword v55, v[40:41] offset:1792
	flat_load_dword v56, v[40:41] offset:2048
	flat_load_dword v57, v[40:41] offset:2304
	flat_load_dword v58, v[40:41] offset:2560
	flat_load_dword v59, v[40:41] offset:2816
	flat_load_dword v60, v[40:41] offset:3072
	flat_load_dword v128, v[40:41] offset:3328
	s_add_u32 s0, s12, 0x1000
	s_addc_u32 s1, s13, 0
	v_lshlrev_b32_e32 v38, 2, v4
	v_mov_b32_e32 v39, v1
	v_lshlrev_b32_e32 v36, 2, v6
	v_mov_b32_e32 v37, v1
	v_lshlrev_b32_e32 v34, 2, v8
	flat_load_dword v129, v[40:41] offset:3584
	flat_load_dword v130, v[40:41] offset:3840
	v_mov_b32_e32 v35, v1
	v_lshl_add_u64 v[40:41], s[0:1], 0, v[0:1]
	v_lshl_add_u64 v[42:43], s[0:1], 0, v[38:39]
	v_lshl_add_u64 v[44:45], s[0:1], 0, v[36:37]
	v_lshl_add_u64 v[46:47], s[0:1], 0, v[34:35]
	flat_load_dword v131, v[40:41]
	flat_load_dword v132, v[42:43]
	flat_load_dword v133, v[44:45]
	flat_load_dword v134, v[46:47]
	s_movk_i32 s2, 0xfff
	s_waitcnt vmcnt(0) lgkmcnt(0)
	v_not_b32_e32 v40, v48
	v_or_b32_e32 v41, 0x80000000, v48
	v_cmp_gt_i32_e32 vcc, 0, v48
	v_not_b32_e32 v42, v49
	v_or_b32_e32 v43, 0x80000000, v49
	v_cndmask_b32_e32 v221, v41, v40, vcc
	v_cmp_gt_i32_e32 vcc, 0, v49
	v_not_b32_e32 v44, v50
	v_or_b32_e32 v45, 0x80000000, v50
	v_cndmask_b32_e32 v220, v43, v42, vcc
	v_cmp_gt_i32_e32 vcc, 0, v50
	v_not_b32_e32 v46, v51
	v_or_b32_e32 v47, 0x80000000, v51
	v_cndmask_b32_e32 v219, v45, v44, vcc
	v_cmp_gt_i32_e32 vcc, 0, v51
	v_not_b32_e32 v61, v52
	v_or_b32_e32 v62, 0x80000000, v52
	v_cndmask_b32_e32 v218, v47, v46, vcc
	v_cmp_gt_i32_e32 vcc, 0, v52
	v_not_b32_e32 v63, v53
	v_or_b32_e32 v135, 0x80000000, v53
	v_cndmask_b32_e32 v217, v62, v61, vcc
	v_cmp_gt_i32_e32 vcc, 0, v53
	v_not_b32_e32 v136, v54
	v_or_b32_e32 v137, 0x80000000, v54
	v_cndmask_b32_e32 v216, v135, v63, vcc
	v_cmp_gt_i32_e32 vcc, 0, v54
	v_not_b32_e32 v138, v55
	v_or_b32_e32 v139, 0x80000000, v55
	v_cndmask_b32_e32 v215, v137, v136, vcc
	v_cmp_gt_i32_e32 vcc, 0, v55
	v_not_b32_e32 v140, v56
	v_or_b32_e32 v141, 0x80000000, v56
	v_cndmask_b32_e32 v214, v139, v138, vcc
	v_cmp_gt_i32_e32 vcc, 0, v56
	v_not_b32_e32 v162, v57
	v_or_b32_e32 v163, 0x80000000, v57
	v_cndmask_b32_e32 v213, v141, v140, vcc
	v_cmp_gt_i32_e32 vcc, 0, v57
	v_not_b32_e32 v164, v58
	v_or_b32_e32 v165, 0x80000000, v58
	v_cndmask_b32_e32 v211, v163, v162, vcc
	v_cmp_gt_i32_e32 vcc, 0, v58
	v_lshlrev_b32_e32 v62, 2, v10
	v_mov_b32_e32 v63, v1
	v_not_b32_e32 v166, v59
	v_or_b32_e32 v167, 0x80000000, v59
	v_cndmask_b32_e32 v206, v165, v164, vcc
	v_cmp_gt_i32_e32 vcc, 0, v59
	v_lshl_add_u64 v[40:41], s[0:1], 0, v[62:63]
	v_not_b32_e32 v168, v60
	v_or_b32_e32 v169, 0x80000000, v60
	v_cndmask_b32_e32 v203, v167, v166, vcc
	flat_load_dword v135, v[40:41]
	v_cmp_gt_i32_e32 vcc, 0, v60
	v_lshlrev_b32_e32 v60, 2, v12
	v_mov_b32_e32 v61, v1
	v_lshl_add_u64 v[40:41], s[0:1], 0, v[60:61]
	flat_load_dword v136, v[40:41]
	v_lshlrev_b32_e32 v58, 2, v14
	v_mov_b32_e32 v59, v1
	v_lshl_add_u64 v[40:41], s[0:1], 0, v[58:59]
	v_lshlrev_b32_e32 v56, 2, v16
	v_mov_b32_e32 v57, v1
	flat_load_dword v137, v[40:41]
	v_lshl_add_u64 v[40:41], s[0:1], 0, v[56:57]
	flat_load_dword v138, v[40:41]
	v_lshlrev_b32_e32 v54, 2, v18
	v_mov_b32_e32 v55, v1
	v_lshl_add_u64 v[40:41], s[0:1], 0, v[54:55]
	v_lshlrev_b32_e32 v52, 2, v20
	v_mov_b32_e32 v53, v1
	flat_load_dword v139, v[40:41]
	v_lshl_add_u64 v[40:41], s[0:1], 0, v[52:53]
	flat_load_dword v140, v[40:41]
	v_lshlrev_b32_e32 v50, 2, v22
	v_mov_b32_e32 v51, v1
	v_lshl_add_u64 v[40:41], s[0:1], 0, v[50:51]
	flat_load_dword v141, v[40:41]
	v_cndmask_b32_e32 v200, v169, v168, vcc
	v_not_b32_e32 v42, v128
	v_or_b32_e32 v43, 0x80000000, v128
	v_cmp_gt_i32_e32 vcc, 0, v128
	v_lshlrev_b32_e32 v48, 2, v24
	v_mov_b32_e32 v49, v1
	v_cndmask_b32_e32 v202, v43, v42, vcc
	v_not_b32_e32 v42, v129
	v_or_b32_e32 v43, 0x80000000, v129
	v_cmp_gt_i32_e32 vcc, 0, v129
	v_lshl_add_u64 v[40:41], s[0:1], 0, v[48:49]
	v_lshlrev_b32_e32 v46, 2, v26
	v_mov_b32_e32 v47, v1
	v_cndmask_b32_e32 v204, v43, v42, vcc
	v_not_b32_e32 v42, v130
	v_or_b32_e32 v43, 0x80000000, v130
	v_cmp_gt_i32_e32 vcc, 0, v130
	flat_load_dword v130, v[40:41]
	v_lshl_add_u64 v[40:41], s[0:1], 0, v[46:47]
	v_lshlrev_b32_e32 v44, 2, v28
	v_mov_b32_e32 v45, v1
	v_cndmask_b32_e32 v207, v43, v42, vcc
	v_not_b32_e32 v42, v131
	v_or_b32_e32 v43, 0x80000000, v131
	flat_load_dword v162, v[40:41]
	v_cmp_gt_i32_e32 vcc, 0, v131
	v_lshl_add_u64 v[40:41], s[0:1], 0, v[44:45]
	flat_load_dword v163, v[40:41]
	v_cndmask_b32_e32 v208, v43, v42, vcc
	v_lshlrev_b32_e32 v42, 2, v30
	v_mov_b32_e32 v43, v1
	v_lshl_add_u64 v[40:41], s[0:1], 0, v[42:43]
	flat_load_dword v164, v[40:41]
	v_lshlrev_b32_e32 v40, 2, v32
	v_mov_b32_e32 v41, v1
	v_lshl_add_u64 v[128:129], s[0:1], 0, v[40:41]
	s_add_u32 s0, s12, 0x2000
	flat_load_dword v166, v[128:129]
	s_addc_u32 s1, s13, 0
	v_not_b32_e32 v131, v132
	v_or_b32_e32 v165, 0x80000000, v132
	v_cmp_gt_i32_e32 vcc, 0, v132
	v_lshl_add_u64 v[128:129], s[0:1], 0, v[0:1]
	flat_load_dword v132, v[128:129]
	v_cndmask_b32_e32 v212, v165, v131, vcc
	v_not_b32_e32 v131, v133
	v_or_b32_e32 v128, 0x80000000, v133
	v_cmp_gt_i32_e32 vcc, 0, v133
	s_nop 1
	v_cndmask_b32_e32 v210, v128, v131, vcc
	v_lshl_add_u64 v[128:129], s[0:1], 0, v[38:39]
	v_not_b32_e32 v131, v134
	flat_load_dword v133, v[128:129]
	v_or_b32_e32 v128, 0x80000000, v134
	v_cmp_gt_i32_e32 vcc, 0, v134
	s_nop 1
	v_cndmask_b32_e32 v209, v128, v131, vcc
	v_lshl_add_u64 v[128:129], s[0:1], 0, v[36:37]
	s_waitcnt vmcnt(0) lgkmcnt(0)
; DI unsigned f2key(float f) { const unsigned u = __float_as_uint(f); return (u & 0x80000000u) ? ~u : (u | 0x80000000u); }
; template <int NV>
; DI void topk_row(const float* row, int s, LAS int* lst, int lane) {
;     ...
;     for (int jo = 0; jo < NV / 16; ++jo) { const float* rb = row + jo * 1024;
; #pragma unroll
;         for (int ji = 0; ji < 16; ++ji) { const int j = jo * 16 + ji; const unsigned u = f2key(rb[ji * 64 + lane]); key[j] = (j * 64 + lane <= s) ? u : 0u; } }
	v_not_b32_e32 v131, v135
	flat_load_dword v134, v[128:129]
	v_or_b32_e32 v128, 0x80000000, v135
	v_cmp_gt_i32_e32 vcc, 0, v135
	s_nop 1
	v_cndmask_b32_e32 v205, v128, v131, vcc
	v_lshl_add_u64 v[128:129], s[0:1], 0, v[34:35]
	v_not_b32_e32 v131, v136
	flat_load_dword v135, v[128:129]
	v_or_b32_e32 v128, 0x80000000, v136
	v_cmp_gt_i32_e32 vcc, 0, v136
	v_or_b32_e32 v136, 0x80000000, v137
	s_nop 0
	v_cndmask_b32_e32 v201, v128, v131, vcc
	v_lshl_add_u64 v[128:129], s[0:1], 0, v[62:63]
	flat_load_dword v165, v[128:129]
	v_not_b32_e32 v131, v137
	v_cmp_gt_i32_e32 vcc, 0, v137
	v_lshl_add_u64 v[128:129], s[0:1], 0, v[60:61]
	v_or_b32_e32 v137, 0x80000000, v139
	v_cndmask_b32_e32 v199, v136, v131, vcc
	v_not_b32_e32 v131, v138
	flat_load_dword v136, v[128:129]
	v_or_b32_e32 v128, 0x80000000, v138
	v_cmp_gt_i32_e32 vcc, 0, v138
	s_nop 1
	v_cndmask_b32_e32 v198, v128, v131, vcc
	v_lshl_add_u64 v[128:129], s[0:1], 0, v[58:59]
	flat_load_dword v138, v[128:129]
	v_lshl_add_u64 v[128:129], s[0:1], 0, v[56:57]
	v_not_b32_e32 v131, v139
	v_cmp_gt_i32_e32 vcc, 0, v139
	flat_load_dword v139, v[128:129]
	v_lshl_add_u64 v[128:129], s[0:1], 0, v[54:55]
	v_cndmask_b32_e32 v197, v137, v131, vcc
	v_not_b32_e32 v131, v140
	v_or_b32_e32 v137, 0x80000000, v140
	v_cmp_gt_i32_e32 vcc, 0, v140
	flat_load_dword v140, v[128:129]
	v_lshl_add_u64 v[128:129], s[0:1], 0, v[52:53]
	v_cndmask_b32_e32 v196, v137, v131, vcc
	v_not_b32_e32 v131, v141
	v_or_b32_e32 v137, 0x80000000, v141
	v_cmp_gt_i32_e32 vcc, 0, v141
	flat_load_dword v141, v[128:129]
	v_lshl_add_u64 v[128:129], s[0:1], 0, v[50:51]
	v_cndmask_b32_e32 v195, v137, v131, vcc
	v_not_b32_e32 v131, v130
	v_or_b32_e32 v137, 0x80000000, v130
	v_cmp_gt_i32_e32 vcc, 0, v130
	v_not_b32_e32 v130, v162
	s_nop 0
	v_cndmask_b32_e32 v194, v137, v131, vcc
	v_or_b32_e32 v131, 0x80000000, v162
	v_cmp_gt_i32_e32 vcc, 0, v162
	flat_load_dword v137, v[128:129]
	v_not_b32_e32 v128, v163
	v_cndmask_b32_e32 v193, v131, v130, vcc
	v_or_b32_e32 v129, 0x80000000, v163
	v_cmp_gt_i32_e32 vcc, 0, v163
	v_not_b32_e32 v130, v164
	s_nop 0
	v_cndmask_b32_e32 v192, v129, v128, vcc
	v_lshl_add_u64 v[128:129], s[0:1], 0, v[48:49]
	flat_load_dword v131, v[128:129]
	v_or_b32_e32 v128, 0x80000000, v164
	v_cmp_gt_i32_e32 vcc, 0, v164
	s_nop 1
	v_cndmask_b32_e32 v191, v128, v130, vcc
	v_lshl_add_u64 v[128:129], s[0:1], 0, v[46:47]
	v_not_b32_e32 v130, v166
	flat_load_dword v162, v[128:129]
	v_or_b32_e32 v128, 0x80000000, v166
	v_cmp_gt_i32_e32 vcc, 0, v166
	s_nop 1
	v_cndmask_b32_e32 v190, v128, v130, vcc
	v_lshl_add_u64 v[128:129], s[0:1], 0, v[44:45]
	flat_load_dword v163, v[128:129]
	v_not_b32_e32 v130, v132
	v_or_b32_e32 v128, 0x80000000, v132
	v_cmp_gt_i32_e32 vcc, 0, v132
	s_nop 1
	v_cndmask_b32_e32 v189, v128, v130, vcc
	v_lshl_add_u64 v[128:129], s[0:1], 0, v[42:43]
	v_not_b32_e32 v130, v133
	flat_load_dword v132, v[128:129]
	v_or_b32_e32 v128, 0x80000000, v133
	v_cmp_gt_i32_e32 vcc, 0, v133
	s_waitcnt vmcnt(0) lgkmcnt(0)
	v_or_b32_e32 v133, 0x80000000, v134
	v_cndmask_b32_e32 v188, v128, v130, vcc
	v_lshl_add_u64 v[128:129], s[0:1], 0, v[40:41]
	s_add_u32 s0, s12, 0x3000
	s_addc_u32 s1, s13, 0
	v_not_b32_e32 v130, v134
	flat_load_dword v164, v[128:129]
	v_cmp_gt_i32_e32 vcc, 0, v134
	v_lshl_add_u64 v[128:129], s[0:1], 0, v[0:1]
	s_nop 0
	v_cndmask_b32_e32 v187, v133, v130, vcc
	v_not_b32_e32 v130, v135
	flat_load_dword v133, v[128:129]
	v_or_b32_e32 v128, 0x80000000, v135
	v_cmp_gt_i32_e32 vcc, 0, v135
	v_or_b32_e32 v129, 0x80000000, v165
	v_or_b32_e32 v135, 0x80000000, v136
	v_cndmask_b32_e32 v186, v128, v130, vcc
	v_not_b32_e32 v128, v165
	v_cmp_gt_i32_e32 vcc, 0, v165
	v_not_b32_e32 v130, v136
	s_nop 0
	v_cndmask_b32_e32 v185, v129, v128, vcc
	v_lshl_add_u64 v[128:129], s[0:1], 0, v[38:39]
	flat_load_dword v134, v[128:129]
	v_lshl_add_u64 v[128:129], s[0:1], 0, v[36:37]
	flat_load_dword v165, v[128:129]
	v_cmp_gt_i32_e32 vcc, 0, v136
	v_lshl_add_u64 v[128:129], s[0:1], 0, v[34:35]
	flat_load_dword v136, v[128:129]
	v_cndmask_b32_e32 v184, v135, v130, vcc
	v_not_b32_e32 v130, v138
	v_or_b32_e32 v135, 0x80000000, v138
	v_cmp_gt_i32_e32 vcc, 0, v138
	v_lshl_add_u64 v[128:129], s[0:1], 0, v[62:63]
	flat_load_dword v138, v[128:129]
	v_cndmask_b32_e32 v183, v135, v130, vcc
	v_not_b32_e32 v130, v139
	v_or_b32_e32 v135, 0x80000000, v139
	v_cmp_gt_i32_e32 vcc, 0, v139
	v_lshl_add_u64 v[128:129], s[0:1], 0, v[60:61]
	s_nop 0
	v_cndmask_b32_e32 v182, v135, v130, vcc
	v_not_b32_e32 v130, v140
	flat_load_dword v135, v[128:129]
	v_or_b32_e32 v128, 0x80000000, v140
	v_cmp_gt_i32_e32 vcc, 0, v140
	s_nop 1
	v_cndmask_b32_e32 v181, v128, v130, vcc
	v_lshl_add_u64 v[128:129], s[0:1], 0, v[58:59]
	v_not_b32_e32 v130, v141
	flat_load_dword v139, v[128:129]
	v_or_b32_e32 v128, 0x80000000, v141
	v_cmp_gt_i32_e32 vcc, 0, v141
	v_or_b32_e32 v141, 0x80000000, v137
	s_nop 0
	v_cndmask_b32_e32 v180, v128, v130, vcc
	v_lshl_add_u64 v[128:129], s[0:1], 0, v[56:57]
	flat_load_dword v140, v[128:129]
	v_lshl_add_u64 v[128:129], s[0:1], 0, v[54:55]
	flat_load_dword v222, v[128:129]
	v_not_b32_e32 v130, v137
	v_cmp_gt_i32_e32 vcc, 0, v137
	v_lshl_add_u64 v[128:129], s[0:1], 0, v[52:53]
	v_or_b32_e32 v137, 0x80000000, v131
	v_cndmask_b32_e32 v179, v141, v130, vcc
	v_not_b32_e32 v130, v131
	flat_load_dword v141, v[128:129]
	v_cmp_gt_i32_e32 vcc, 0, v131
	v_lshl_add_u64 v[128:129], s[0:1], 0, v[50:51]
	v_or_b32_e32 v131, 0x80000000, v162
	v_cndmask_b32_e32 v178, v137, v130, vcc
	v_not_b32_e32 v130, v162
	flat_load_dword v137, v[128:129]
	v_cmp_gt_i32_e32 vcc, 0, v162
	v_lshl_add_u64 v[128:129], s[0:1], 0, v[48:49]
	v_or_b32_e32 v162, 0x80000000, v132
	v_cndmask_b32_e32 v177, v131, v130, vcc
	v_not_b32_e32 v130, v163
	flat_load_dword v131, v[128:129]
	v_or_b32_e32 v128, 0x80000000, v163
	v_cmp_gt_i32_e32 vcc, 0, v163
	s_nop 1
	v_cndmask_b32_e32 v176, v128, v130, vcc
	v_lshl_add_u64 v[128:129], s[0:1], 0, v[46:47]
	flat_load_dword v223, v[128:129]
	v_lshl_add_u64 v[128:129], s[0:1], 0, v[44:45]
	flat_load_dword v224, v[128:129]
	v_lshl_add_u64 v[128:129], s[0:1], 0, v[42:43]
	flat_load_dword v225, v[128:129]
	v_lshl_add_u64 v[128:129], s[0:1], 0, v[40:41]
	s_add_u32 s0, s12, 0x4000
	v_not_b32_e32 v130, v132
	v_cmp_gt_i32_e32 vcc, 0, v132
	flat_load_dword v226, v[128:129]
	s_addc_u32 s1, s13, 0
	v_cndmask_b32_e32 v175, v162, v130, vcc
	s_waitcnt vmcnt(0) lgkmcnt(0)
; DI unsigned f2key(float f) { const unsigned u = __float_as_uint(f); return (u & 0x80000000u) ? ~u : (u | 0x80000000u); }
; template <int NV>
; DI void topk_row(const float* row, int s, LAS int* lst, int lane) {
;     ...
;     for (int jo = 0; jo < NV / 16; ++jo) { const float* rb = row + jo * 1024;
; #pragma unroll
;         for (int ji = 0; ji < 16; ++ji) { const int j = jo * 16 + ji; const unsigned u = f2key(rb[ji * 64 + lane]); key[j] = (j * 64 + lane <= s) ? u : 0u; } }
	v_not_b32_e32 v130, v164
	v_or_b32_e32 v132, 0x80000000, v164
	v_cmp_gt_i32_e32 vcc, 0, v164
	v_lshl_add_u64 v[128:129], s[0:1], 0, v[0:1]
	flat_load_dword v227, v[128:129]
	v_cndmask_b32_e32 v173, v132, v130, vcc
	v_not_b32_e32 v130, v133
	v_or_b32_e32 v132, 0x80000000, v133
	v_cmp_gt_i32_e32 vcc, 0, v133
	v_not_b32_e32 v128, v134
	v_or_b32_e32 v129, 0x80000000, v134
	v_cndmask_b32_e32 v174, v132, v130, vcc
	v_cmp_gt_i32_e32 vcc, 0, v134
	v_not_b32_e32 v130, v165
	v_or_b32_e32 v133, 0x80000000, v136
	v_cndmask_b32_e32 v172, v129, v128, vcc
	v_lshl_add_u64 v[128:129], s[0:1], 0, v[38:39]
	flat_load_dword v132, v[128:129]
	v_or_b32_e32 v128, 0x80000000, v165
	v_cmp_gt_i32_e32 vcc, 0, v165
	s_nop 1
	v_cndmask_b32_e32 v171, v128, v130, vcc
	v_not_b32_e32 v130, v136
	v_lshl_add_u64 v[128:129], s[0:1], 0, v[36:37]
	v_cmp_gt_i32_e32 vcc, 0, v136
	flat_load_dword v134, v[128:129]
	v_not_b32_e32 v128, v138
	v_cndmask_b32_e32 v170, v133, v130, vcc
	v_or_b32_e32 v129, 0x80000000, v138
	v_cmp_gt_i32_e32 vcc, 0, v138
	v_not_b32_e32 v130, v135
	s_nop 0
	v_cndmask_b32_e32 v169, v129, v128, vcc
	v_lshl_add_u64 v[128:129], s[0:1], 0, v[34:35]
	flat_load_dword v133, v[128:129]
	v_or_b32_e32 v128, 0x80000000, v135
	v_cmp_gt_i32_e32 vcc, 0, v135
	v_or_b32_e32 v135, 0x80000000, v139
	s_nop 0
	v_cndmask_b32_e32 v168, v128, v130, vcc
	v_not_b32_e32 v130, v139
	v_lshl_add_u64 v[128:129], s[0:1], 0, v[62:63]
	v_cmp_gt_i32_e32 vcc, 0, v139
	flat_load_dword v228, v[128:129]
	v_not_b32_e32 v128, v140
	v_cndmask_b32_e32 v167, v135, v130, vcc
	v_or_b32_e32 v129, 0x80000000, v140
	v_cmp_gt_i32_e32 vcc, 0, v140
	v_not_b32_e32 v130, v222
	v_or_b32_e32 v135, 0x80000000, v141
	v_cndmask_b32_e32 v166, v129, v128, vcc
	v_lshl_add_u64 v[128:129], s[0:1], 0, v[60:61]
	flat_load_dword v229, v[128:129]
	v_or_b32_e32 v128, 0x80000000, v222
	v_cmp_gt_i32_e32 vcc, 0, v222
	s_nop 1
	v_cndmask_b32_e32 v165, v128, v130, vcc
	v_lshl_add_u64 v[128:129], s[0:1], 0, v[58:59]
	flat_load_dword v222, v[128:129]
	v_not_b32_e32 v130, v141
	v_cmp_gt_i32_e32 vcc, 0, v141
	v_not_b32_e32 v128, v137
	v_or_b32_e32 v129, 0x80000000, v137
	v_cndmask_b32_e32 v164, v135, v130, vcc
	v_cmp_gt_i32_e32 vcc, 0, v137
	v_not_b32_e32 v130, v131
	v_or_b32_e32 v135, 0x80000000, v131
	v_cndmask_b32_e32 v163, v129, v128, vcc
	v_lshl_add_u64 v[128:129], s[0:1], 0, v[56:57]
	v_cmp_gt_i32_e32 vcc, 0, v131
	flat_load_dword v230, v[128:129]
	v_not_b32_e32 v128, v223
	v_cndmask_b32_e32 v162, v135, v130, vcc
	v_or_b32_e32 v129, 0x80000000, v223
	v_cmp_gt_i32_e32 vcc, 0, v223
	v_not_b32_e32 v130, v224
	s_waitcnt vmcnt(0) lgkmcnt(0)
	v_or_b32_e32 v131, 0x80000000, v134
	v_cndmask_b32_e32 v141, v129, v128, vcc
	v_lshl_add_u64 v[128:129], s[0:1], 0, v[54:55]
	flat_load_dword v223, v[128:129]
	v_or_b32_e32 v128, 0x80000000, v224
	v_cmp_gt_i32_e32 vcc, 0, v224
	s_nop 1
	v_cndmask_b32_e32 v140, v128, v130, vcc
	v_lshl_add_u64 v[128:129], s[0:1], 0, v[52:53]
	v_not_b32_e32 v130, v225
	flat_load_dword v224, v[128:129]
	v_or_b32_e32 v128, 0x80000000, v225
	v_cmp_gt_i32_e32 vcc, 0, v225
	v_or_b32_e32 v129, 0x80000000, v226
	s_nop 0
	v_cndmask_b32_e32 v139, v128, v130, vcc
	v_not_b32_e32 v128, v226
	v_cmp_gt_i32_e32 vcc, 0, v226
	v_not_b32_e32 v130, v227
	s_nop 0
	v_cndmask_b32_e32 v138, v129, v128, vcc
	v_lshl_add_u64 v[128:129], s[0:1], 0, v[50:51]
	flat_load_dword v225, v[128:129]
	v_or_b32_e32 v128, 0x80000000, v227
	v_cmp_gt_i32_e32 vcc, 0, v227
	s_nop 1
	v_cndmask_b32_e32 v128, v128, v130, vcc
	v_cmp_lt_u32_e32 vcc, s2, v161
	v_not_b32_e32 v130, v132
	s_movk_i32 s2, 0x103f
	v_cndmask_b32_e32 v137, 0, v128, vcc
	v_lshl_add_u64 v[128:129], s[0:1], 0, v[48:49]
	flat_load_dword v226, v[128:129]
	v_or_b32_e32 v128, 0x80000000, v132
	v_cmp_gt_i32_e32 vcc, 0, v132
	s_nop 1
	v_cndmask_b32_e32 v128, v128, v130, vcc
	v_cmp_lt_u32_e32 vcc, s2, v161
	v_not_b32_e32 v130, v134
	s_movk_i32 s2, 0x107f
	v_cndmask_b32_e32 v136, 0, v128, vcc
	v_lshl_add_u64 v[128:129], s[0:1], 0, v[46:47]
	flat_load_dword v227, v[128:129]
	v_cmp_gt_i32_e32 vcc, 0, v134
	s_nop 1
	v_cndmask_b32_e32 v128, v131, v130, vcc
	v_cmp_lt_u32_e32 vcc, s2, v161
	v_not_b32_e32 v130, v133
	v_or_b32_e32 v131, 0x80000000, v133
	v_cndmask_b32_e32 v135, 0, v128, vcc
	v_lshl_add_u64 v[128:129], s[0:1], 0, v[44:45]
	v_cmp_gt_i32_e32 vcc, 0, v133
	s_movk_i32 s2, 0x10bf
	flat_load_dword v231, v[128:129]
	v_cndmask_b32_e32 v128, v131, v130, vcc
	v_cmp_lt_u32_e32 vcc, s2, v161
	v_or_b32_e32 v129, 0x80000000, v228
	s_movk_i32 s2, 0x10ff
	v_cndmask_b32_e32 v134, 0, v128, vcc
	v_not_b32_e32 v128, v228
	v_cmp_gt_i32_e32 vcc, 0, v228
	s_nop 1
	v_cndmask_b32_e32 v130, v129, v128, vcc
	v_lshl_add_u64 v[128:129], s[0:1], 0, v[42:43]
	v_cmp_lt_u32_e32 vcc, s2, v161
	flat_load_dword v228, v[128:129]
	v_not_b32_e32 v128, v229
	v_cndmask_b32_e32 v132, 0, v130, vcc
	v_or_b32_e32 v129, 0x80000000, v229
	v_cmp_gt_i32_e32 vcc, 0, v229
	s_movk_i32 s2, 0x117f
	s_nop 0
	v_cndmask_b32_e32 v130, v129, v128, vcc
	v_lshl_add_u64 v[128:129], s[0:1], 0, v[40:41]
	s_movk_i32 s0, 0x113f
	v_cmp_lt_u32_e32 vcc, s0, v161
	s_add_u32 s0, s12, 0x5000
	flat_load_dword v229, v[128:129]
	s_addc_u32 s1, s13, 0
	v_lshl_add_u64 v[38:39], s[0:1], 0, v[38:39]
	v_cndmask_b32_e32 v130, 0, v130, vcc
	v_cmp_gt_i32_e32 vcc, 0, v222
	flat_load_dword v38, v[38:39]
	v_not_b32_e32 v128, v222
	v_or_b32_e32 v129, 0x80000000, v222
	v_cndmask_b32_e32 v131, v129, v128, vcc
	v_lshl_add_u64 v[128:129], s[0:1], 0, v[0:1]
	flat_load_dword v0, v[128:129]
	v_cmp_lt_u32_e32 vcc, s2, v161
	v_not_b32_e32 v128, v230
	v_or_b32_e32 v129, 0x80000000, v230
	v_cndmask_b32_e32 v133, 0, v131, vcc
	v_cmp_gt_i32_e32 vcc, 0, v230
	s_movk_i32 s2, 0x11bf
	v_lshl_add_u64 v[36:37], s[0:1], 0, v[36:37]
	v_cndmask_b32_e32 v128, v129, v128, vcc
	v_cmp_lt_u32_e32 vcc, s2, v161
	s_movk_i32 s2, 0x11ff
	flat_load_dword v36, v[36:37]
	v_cndmask_b32_e32 v131, 0, v128, vcc
	s_waitcnt vmcnt(0) lgkmcnt(0)
; DI unsigned f2key(float f) { const unsigned u = __float_as_uint(f); return (u & 0x80000000u) ? ~u : (u | 0x80000000u); }
; template <int NV>
; DI void topk_row(const float* row, int s, LAS int* lst, int lane) {
;     ...
;     for (int jo = 0; jo < NV / 16; ++jo) { const float* rb = row + jo * 1024;
; #pragma unroll
;         for (int ji = 0; ji < 16; ++ji) { const int j = jo * 16 + ji; const unsigned u = f2key(rb[ji * 64 + lane]); key[j] = (j * 64 + lane <= s) ? u : 0u; } }
	v_not_b32_e32 v39, v223
	v_or_b32_e32 v128, 0x80000000, v223
	v_cmp_gt_i32_e32 vcc, 0, v223
	v_or_b32_e32 v37, 0x80000000, v224
	v_lshl_add_u64 v[34:35], s[0:1], 0, v[34:35]
	v_cndmask_b32_e32 v39, v128, v39, vcc
	v_cmp_lt_u32_e32 vcc, s2, v161
	s_movk_i32 s2, 0x123f
	v_or_b32_e32 v222, 0x80000000, v225
	v_cndmask_b32_e32 v128, 0, v39, vcc
	v_not_b32_e32 v39, v224
	v_cmp_gt_i32_e32 vcc, 0, v224
	s_nop 1
	v_cndmask_b32_e32 v37, v37, v39, vcc
	flat_load_dword v39, v[34:35]
	v_cmp_lt_u32_e32 vcc, s2, v161
	v_lshl_add_u64 v[34:35], s[0:1], 0, v[62:63]
	s_movk_i32 s2, 0x127f
	v_cndmask_b32_e32 v129, 0, v37, vcc
	v_not_b32_e32 v37, v225
	v_cmp_gt_i32_e32 vcc, 0, v225
	flat_load_dword v63, v[34:35]
	s_nop 0
	v_cndmask_b32_e32 v34, v222, v37, vcc
	v_cmp_lt_u32_e32 vcc, s2, v161
	v_not_b32_e32 v37, v226
	s_movk_i32 s2, 0x12bf
	v_cndmask_b32_e32 v62, 0, v34, vcc
	v_lshl_add_u64 v[34:35], s[0:1], 0, v[60:61]
	flat_load_dword v60, v[34:35]
	v_or_b32_e32 v34, 0x80000000, v226
	v_cmp_gt_i32_e32 vcc, 0, v226
	v_or_b32_e32 v61, 0x80000000, v227
	s_nop 0
	v_cndmask_b32_e32 v37, v34, v37, vcc
	v_lshl_add_u64 v[34:35], s[0:1], 0, v[58:59]
	flat_load_dword v59, v[34:35]
	v_cmp_lt_u32_e32 vcc, s2, v161
	v_lshl_add_u64 v[34:35], s[0:1], 0, v[56:57]
	s_movk_i32 s2, 0x12ff
	v_cndmask_b32_e32 v58, 0, v37, vcc
	v_not_b32_e32 v37, v227
	v_cmp_gt_i32_e32 vcc, 0, v227
	flat_load_dword v57, v[34:35]
	s_nop 0
	v_cndmask_b32_e32 v34, v61, v37, vcc
	v_cmp_lt_u32_e32 vcc, s2, v161
	v_not_b32_e32 v37, v231
	s_movk_i32 s2, 0x133f
	v_cndmask_b32_e32 v56, 0, v34, vcc
	v_lshl_add_u64 v[34:35], s[0:1], 0, v[54:55]
	flat_load_dword v54, v[34:35]
	v_or_b32_e32 v34, 0x80000000, v231
	v_cmp_gt_i32_e32 vcc, 0, v231
	v_or_b32_e32 v55, 0x80000000, v228
	s_nop 0
	v_cndmask_b32_e32 v37, v34, v37, vcc
	v_lshl_add_u64 v[34:35], s[0:1], 0, v[52:53]
	flat_load_dword v53, v[34:35]
	v_cmp_lt_u32_e32 vcc, s2, v161
	v_lshl_add_u64 v[34:35], s[0:1], 0, v[50:51]
	s_movk_i32 s2, 0x137f
	v_cndmask_b32_e32 v52, 0, v37, vcc
	v_not_b32_e32 v37, v228
	v_cmp_gt_i32_e32 vcc, 0, v228
	flat_load_dword v61, v[34:35]
	s_nop 0
	v_cndmask_b32_e32 v34, v55, v37, vcc
	v_cmp_lt_u32_e32 vcc, s2, v161
	v_not_b32_e32 v37, v229
	s_movk_i32 s2, 0x13bf
	v_cndmask_b32_e32 v50, 0, v34, vcc
	v_lshl_add_u64 v[34:35], s[0:1], 0, v[48:49]
	flat_load_dword v55, v[34:35]
	v_or_b32_e32 v34, 0x80000000, v229
	v_cmp_gt_i32_e32 vcc, 0, v229
	s_nop 1
	v_cndmask_b32_e32 v37, v34, v37, vcc
	v_lshl_add_u64 v[34:35], s[0:1], 0, v[46:47]
	flat_load_dword v222, v[34:35]
	v_cmp_lt_u32_e32 vcc, s2, v161
	v_lshl_add_u64 v[34:35], s[0:1], 0, v[44:45]
	v_or_b32_e32 v46, 0x80000000, v0
	v_cndmask_b32_e32 v49, 0, v37, vcc
	v_not_b32_e32 v37, v0
	flat_load_dword v223, v[34:35]
	v_cmp_gt_i32_e32 vcc, 0, v0
	s_movk_i32 s2, 0x13ff
	v_lshl_add_u64 v[34:35], s[0:1], 0, v[42:43]
	v_cndmask_b32_e32 v0, v46, v37, vcc
	v_cmp_lt_u32_e32 vcc, s2, v161
	flat_load_dword v224, v[34:35]
	v_or_b32_e32 v34, 0x80000000, v38
	v_cndmask_b32_e32 v48, 0, v0, vcc
	v_not_b32_e32 v0, v38
	v_cmp_gt_i32_e32 vcc, 0, v38
	s_nop 1
	v_cndmask_b32_e32 v0, v34, v0, vcc
	v_lshl_add_u64 v[34:35], s[0:1], 0, v[40:41]
	flat_load_dword v34, v[34:35]
	s_movk_i32 s0, 0x143f
	v_cmp_lt_u32_e32 vcc, s0, v161
	v_or_b32_e32 v35, 0x80000000, v36
	s_movk_i32 s0, 0x147f
	v_cndmask_b32_e32 v51, 0, v0, vcc
	v_not_b32_e32 v0, v36
	v_cmp_gt_i32_e32 vcc, 0, v36
	s_nop 1
	v_cndmask_b32_e32 v0, v35, v0, vcc
	v_cmp_lt_u32_e32 vcc, s0, v161
	s_waitcnt vmcnt(0) lgkmcnt(0)
	v_or_b32_e32 v35, 0x80000000, v39
	s_movk_i32 s0, 0x14bf
	v_cndmask_b32_e32 v47, 0, v0, vcc
	v_not_b32_e32 v0, v39
	v_cmp_gt_i32_e32 vcc, 0, v39
	s_nop 1
	v_cndmask_b32_e32 v0, v35, v0, vcc
	v_cmp_lt_u32_e32 vcc, s0, v161
	v_or_b32_e32 v35, 0x80000000, v63
	s_movk_i32 s0, 0x14ff
	v_cndmask_b32_e32 v46, 0, v0, vcc
	v_not_b32_e32 v0, v63
	v_cmp_gt_i32_e32 vcc, 0, v63
	s_nop 1
	v_cndmask_b32_e32 v0, v35, v0, vcc
	v_cmp_lt_u32_e32 vcc, s0, v161
	v_or_b32_e32 v35, 0x80000000, v60
	s_movk_i32 s0, 0x153f
	v_cndmask_b32_e32 v45, 0, v0, vcc
	v_not_b32_e32 v0, v60
	v_cmp_gt_i32_e32 vcc, 0, v60
	s_nop 1
	v_cndmask_b32_e32 v0, v35, v0, vcc
	v_cmp_lt_u32_e32 vcc, s0, v161
	v_or_b32_e32 v35, 0x80000000, v59
	s_movk_i32 s0, 0x157f
	v_cndmask_b32_e32 v44, 0, v0, vcc
	v_not_b32_e32 v0, v59
	v_cmp_gt_i32_e32 vcc, 0, v59
	s_nop 1
	v_cndmask_b32_e32 v0, v35, v0, vcc
	v_cmp_lt_u32_e32 vcc, s0, v161
	v_or_b32_e32 v35, 0x80000000, v57
	s_movk_i32 s0, 0x15bf
	v_cndmask_b32_e32 v43, 0, v0, vcc
	v_not_b32_e32 v0, v57
	v_cmp_gt_i32_e32 vcc, 0, v57
	s_nop 1
	v_cndmask_b32_e32 v0, v35, v0, vcc
	v_cmp_lt_u32_e32 vcc, s0, v161
	v_or_b32_e32 v35, 0x80000000, v54
	s_movk_i32 s0, 0x15ff
	v_cndmask_b32_e32 v42, 0, v0, vcc
	v_not_b32_e32 v0, v54
	v_cmp_gt_i32_e32 vcc, 0, v54
	s_nop 1
	v_cndmask_b32_e32 v0, v35, v0, vcc
	v_cmp_lt_u32_e32 vcc, s0, v161
	v_or_b32_e32 v35, 0x80000000, v53
	s_movk_i32 s0, 0x163f
	v_cndmask_b32_e32 v41, 0, v0, vcc
	v_not_b32_e32 v0, v53
	v_cmp_gt_i32_e32 vcc, 0, v53
	v_or_b32_e32 v53, 0x80000000, v34
	s_nop 0
	v_cndmask_b32_e32 v0, v35, v0, vcc
	v_cmp_lt_u32_e32 vcc, s0, v161
	v_or_b32_e32 v35, 0x80000000, v61
	s_movk_i32 s0, 0x167f
	v_cndmask_b32_e32 v40, 0, v0, vcc
	v_not_b32_e32 v0, v61
	v_cmp_gt_i32_e32 vcc, 0, v61
	s_nop 1
	v_cndmask_b32_e32 v0, v35, v0, vcc
	v_cmp_lt_u32_e32 vcc, s0, v161
	v_or_b32_e32 v35, 0x80000000, v55
; DI unsigned f2key(float f) { const unsigned u = __float_as_uint(f); return (u & 0x80000000u) ? ~u : (u | 0x80000000u); }
; template <int NV>
; DI void topk_row(const float* row, int s, LAS int* lst, int lane) {
;     ...
;     for (int jo = 0; jo < NV / 16; ++jo) { const float* rb = row + jo * 1024;
; #pragma unroll
;         for (int ji = 0; ji < 16; ++ji) { const int j = jo * 16 + ji; const unsigned u = f2key(rb[ji * 64 + lane]); key[j] = (j * 64 + lane <= s) ? u : 0u; } }
;     unsigned T = 0u;
; #pragma unroll 1
	s_movk_i32 s0, 0x16bf
	v_cndmask_b32_e32 v39, 0, v0, vcc
	v_not_b32_e32 v0, v55
	v_cmp_gt_i32_e32 vcc, 0, v55
	s_nop 1
	v_cndmask_b32_e32 v0, v35, v0, vcc
	v_cmp_lt_u32_e32 vcc, s0, v161
	v_or_b32_e32 v35, 0x80000000, v222
	s_movk_i32 s0, 0x16ff
	v_cndmask_b32_e32 v38, 0, v0, vcc
	v_not_b32_e32 v0, v222
	v_cmp_gt_i32_e32 vcc, 0, v222
	s_nop 1
	v_cndmask_b32_e32 v0, v35, v0, vcc
	v_cmp_lt_u32_e32 vcc, s0, v161
	v_or_b32_e32 v35, 0x80000000, v223
	s_movk_i32 s0, 0x173f
	v_cndmask_b32_e32 v37, 0, v0, vcc
	v_not_b32_e32 v0, v223
	v_cmp_gt_i32_e32 vcc, 0, v223
	s_nop 1
	v_cndmask_b32_e32 v0, v35, v0, vcc
	v_cmp_lt_u32_e32 vcc, s0, v161
	v_or_b32_e32 v35, 0x80000000, v224
	s_movk_i32 s0, 0x177f
	v_cndmask_b32_e32 v36, 0, v0, vcc
	v_not_b32_e32 v0, v224
	v_cmp_gt_i32_e32 vcc, 0, v224
	s_nop 1
	v_cndmask_b32_e32 v0, v35, v0, vcc
	v_cmp_lt_u32_e32 vcc, s0, v161
	s_movk_i32 s0, 0x17bf
	s_nop 0
	v_cndmask_b32_e32 v35, 0, v0, vcc
	v_not_b32_e32 v0, v34
	v_cmp_gt_i32_e32 vcc, 0, v34
	v_mov_b32_e32 v34, 0
	s_nop 0
	v_cndmask_b32_e32 v0, v53, v0, vcc
	v_cmp_lt_u32_e32 vcc, s0, v161
	v_mov_b32_e32 v53, 31
	s_nop 0
	v_cndmask_b32_e32 v0, 0, v0, vcc
	v_max_u32_e32 v54, v221, v217
	v_max_u32_e32 v55, v220, v216
	v_max_u32_e32 v34, v219, v215
	v_max_u32_e32 v53, v218, v214
	v_max_u32_e32 v54, v54, v213
	v_max_u32_e32 v55, v55, v211
	v_max_u32_e32 v34, v34, v206
	v_max_u32_e32 v53, v53, v203
	v_max_u32_e32 v54, v54, v200
	v_max_u32_e32 v55, v55, v202
	v_max_u32_e32 v34, v34, v204
	v_max_u32_e32 v53, v53, v207
	v_max_u32_e32 v54, v54, v208
	v_max_u32_e32 v55, v55, v212
	v_max_u32_e32 v34, v34, v210
	v_max_u32_e32 v53, v53, v209
	v_max_u32_e32 v54, v54, v205
	v_max_u32_e32 v55, v55, v201
	v_max_u32_e32 v34, v34, v199
	v_max_u32_e32 v53, v53, v198
	v_max_u32_e32 v54, v54, v197
	v_max_u32_e32 v55, v55, v196
	v_max_u32_e32 v34, v34, v195
	v_max_u32_e32 v53, v53, v194
	v_max_u32_e32 v54, v54, v193
	v_max_u32_e32 v55, v55, v192
	v_max_u32_e32 v34, v34, v191
	v_max_u32_e32 v53, v53, v190
	v_max_u32_e32 v54, v54, v189
	v_max_u32_e32 v55, v55, v188
	v_max_u32_e32 v34, v34, v187
	v_max_u32_e32 v53, v53, v186
	v_max_u32_e32 v54, v54, v185
	v_max_u32_e32 v55, v55, v184
	v_max_u32_e32 v34, v34, v183
	v_max_u32_e32 v53, v53, v182
	v_max_u32_e32 v54, v54, v181
	v_max_u32_e32 v55, v55, v180
	v_max_u32_e32 v34, v34, v179
	v_max_u32_e32 v53, v53, v178
	v_max_u32_e32 v54, v54, v177
	v_max_u32_e32 v55, v55, v176
	v_max_u32_e32 v34, v34, v175
	v_max_u32_e32 v53, v53, v173
	v_max_u32_e32 v54, v54, v174
	v_max_u32_e32 v55, v55, v172
	v_max_u32_e32 v34, v34, v171
	v_max_u32_e32 v53, v53, v170
	v_max_u32_e32 v54, v54, v169
	v_max_u32_e32 v55, v55, v168
	v_max_u32_e32 v34, v34, v167
	v_max_u32_e32 v53, v53, v166
	v_max_u32_e32 v54, v54, v165
	v_max_u32_e32 v55, v55, v164
	v_max_u32_e32 v34, v34, v163
	v_max_u32_e32 v53, v53, v162
	v_max_u32_e32 v54, v54, v141
	v_max_u32_e32 v55, v55, v140
	v_max_u32_e32 v34, v34, v139
	v_max_u32_e32 v53, v53, v138
	v_max_u32_e32 v54, v54, v137
	v_max_u32_e32 v55, v55, v136
	v_max_u32_e32 v34, v34, v135
	v_max_u32_e32 v53, v53, v134
	v_max_u32_e32 v54, v54, v132
	v_max_u32_e32 v55, v55, v130
	v_max_u32_e32 v34, v34, v133
	v_max_u32_e32 v53, v53, v131
	v_max_u32_e32 v54, v54, v128
	v_max_u32_e32 v55, v55, v129
	v_max_u32_e32 v34, v34, v62
	v_max_u32_e32 v53, v53, v58
	v_max_u32_e32 v54, v54, v56
	v_max_u32_e32 v55, v55, v52
	v_max_u32_e32 v34, v34, v50
	v_max_u32_e32 v53, v53, v49
	v_max_u32_e32 v54, v54, v48
	v_max_u32_e32 v55, v55, v51
	v_max_u32_e32 v34, v34, v47
	v_max_u32_e32 v53, v53, v46
	v_max_u32_e32 v54, v54, v45
	v_max_u32_e32 v55, v55, v44
	v_max_u32_e32 v34, v34, v43
	v_max_u32_e32 v53, v53, v42
	v_max_u32_e32 v54, v54, v41
	v_max_u32_e32 v55, v55, v40
	v_max_u32_e32 v34, v34, v39
	v_max_u32_e32 v53, v53, v38
	v_max_u32_e32 v54, v54, v37
	v_max_u32_e32 v55, v55, v36
	v_max_u32_e32 v34, v34, v35
	v_max_u32_e32 v53, v53, v0
	v_max3_u32 v255, v54, v55, v34
	v_min3_u32 v54, v54, v55, v34
	v_max_u32_e32 v255, v255, v53
	v_min_u32_e32 v54, v54, v53
	s_nop 1
	v_max_u32_dpp v255, v255, v255 quad_perm:[1,0,3,2] row_mask:0xf bank_mask:0xf bound_ctrl:1
	v_min_u32_dpp v54, v54, v54 quad_perm:[1,0,3,2] row_mask:0xf bank_mask:0xf bound_ctrl:1
	s_nop 1
	v_max_u32_dpp v255, v255, v255 quad_perm:[2,3,0,1] row_mask:0xf bank_mask:0xf bound_ctrl:1
	v_min_u32_dpp v54, v54, v54 quad_perm:[2,3,0,1] row_mask:0xf bank_mask:0xf bound_ctrl:1
	s_nop 1
	v_max_u32_dpp v255, v255, v255 row_half_mirror row_mask:0xf bank_mask:0xf bound_ctrl:1
	v_min_u32_dpp v54, v54, v54 row_half_mirror row_mask:0xf bank_mask:0xf bound_ctrl:1
	s_nop 1
	v_max_u32_dpp v255, v255, v255 row_mirror row_mask:0xf bank_mask:0xf bound_ctrl:1
	v_min_u32_dpp v54, v54, v54 row_mirror row_mask:0xf bank_mask:0xf bound_ctrl:1
	s_nop 1
	v_readlane_b32 s0, v255, 0
	v_readlane_b32 s1, v255, 16
	s_max_u32 s0, s0, s1
	v_readlane_b32 s1, v255, 32
	s_max_u32 s0, s0, s1
	v_readlane_b32 s1, v255, 48
	s_max_u32 s100, s0, s1
	v_readlane_b32 s0, v54, 0
	v_readlane_b32 s1, v54, 16
	s_min_u32 s0, s0, s1
	v_readlane_b32 s1, v54, 32
	s_min_u32 s0, s0, s1
	v_readlane_b32 s1, v54, 48
	s_min_u32 s101, s0, s1
	s_xor_b32 s0, s100, s101
	s_max_u32 s0, s0, 1
	s_flbit_i32_b32 s1, s0
	s_sub_u32 s1, 31, s1
	s_lshl_b32 s0, 1, s1
	s_lshl_b32 s0, s0, 1
	s_sub_u32 s0, s0, 1
	s_andn2_b32 s0, s100, s0
	v_mov_b32_e32 v34, s0
	v_mov_b32_e32 v53, s1

; DI unsigned f2key(float f) { const unsigned u = __float_as_uint(f); return (u & 0x80000000u) ? ~u : (u | 0x80000000u); }
; template <int NV>
; DI void topk_row(const float* row, int s, LAS int* lst, int lane) {
;     ...
;     for (int jo = 0; jo < NV / 16; ++jo) { const float* rb = row + jo * 1024;
; #pragma unroll
;         for (int ji = 0; ji < 16; ++ji) { const int j = jo * 16 + ji; const unsigned u = f2key(rb[ji * 64 + lane]); key[j] = (j * 64 + lane <= s) ? u : 0u; } }
; DI void topk_phase(const float* SC, unsigned short* IDX, LAS unsigned char* lds, int tid, int bid, int G) {
;     ...
;             else if (s < 4096) topk_row<64>(row, s, lst, lane);
.LBB0_2870:
	v_lshlrev_b32_e32 v0, 2, v2
	v_lshl_add_u64 v[40:41], s[12:13], 0, v[0:1]
	flat_load_dword v48, v[40:41]
	flat_load_dword v49, v[40:41] offset:256
	flat_load_dword v50, v[40:41] offset:512
	flat_load_dword v51, v[40:41] offset:768
	flat_load_dword v52, v[40:41] offset:1024
	flat_load_dword v53, v[40:41] offset:1280
	flat_load_dword v54, v[40:41] offset:1536
	flat_load_dword v55, v[40:41] offset:1792
	flat_load_dword v56, v[40:41] offset:2048
	flat_load_dword v57, v[40:41] offset:2304
	flat_load_dword v58, v[40:41] offset:2560
	flat_load_dword v59, v[40:41] offset:2816
	flat_load_dword v60, v[40:41] offset:3072
	flat_load_dword v128, v[40:41] offset:3328
	s_add_u32 s0, s12, 0x1000
	flat_load_dword v129, v[40:41] offset:3584
	flat_load_dword v130, v[40:41] offset:3840
	s_addc_u32 s1, s13, 0
	v_lshlrev_b32_e32 v38, 2, v4
	v_mov_b32_e32 v39, v1
	v_lshlrev_b32_e32 v36, 2, v6
	v_mov_b32_e32 v37, v1
	v_lshlrev_b32_e32 v34, 2, v8
	v_mov_b32_e32 v35, v1
	v_lshl_add_u64 v[40:41], s[0:1], 0, v[0:1]
	v_lshl_add_u64 v[42:43], s[0:1], 0, v[38:39]
	v_lshl_add_u64 v[44:45], s[0:1], 0, v[36:37]
	v_lshl_add_u64 v[46:47], s[0:1], 0, v[34:35]
	flat_load_dword v131, v[40:41]
	flat_load_dword v132, v[42:43]
	flat_load_dword v133, v[44:45]
	flat_load_dword v134, v[46:47]
	s_movk_i32 s2, 0x7ff
	s_waitcnt vmcnt(0) lgkmcnt(0)
	v_not_b32_e32 v40, v48
	v_or_b32_e32 v41, 0x80000000, v48
	v_cmp_gt_i32_e32 vcc, 0, v48
	v_not_b32_e32 v42, v49
	v_or_b32_e32 v43, 0x80000000, v49
	v_cndmask_b32_e32 v189, v41, v40, vcc
	v_cmp_gt_i32_e32 vcc, 0, v49
	v_not_b32_e32 v44, v50
	v_or_b32_e32 v45, 0x80000000, v50
	v_cndmask_b32_e32 v188, v43, v42, vcc
	v_cmp_gt_i32_e32 vcc, 0, v50
	v_not_b32_e32 v46, v51
	v_or_b32_e32 v47, 0x80000000, v51
	v_cndmask_b32_e32 v187, v45, v44, vcc
	v_cmp_gt_i32_e32 vcc, 0, v51
	v_not_b32_e32 v61, v52
	v_or_b32_e32 v62, 0x80000000, v52
	v_cndmask_b32_e32 v186, v47, v46, vcc
	v_cmp_gt_i32_e32 vcc, 0, v52
	v_not_b32_e32 v63, v53
	v_or_b32_e32 v135, 0x80000000, v53
	v_cndmask_b32_e32 v185, v62, v61, vcc
	v_cmp_gt_i32_e32 vcc, 0, v53
	v_not_b32_e32 v136, v54
	v_or_b32_e32 v137, 0x80000000, v54
	v_cndmask_b32_e32 v184, v135, v63, vcc
	v_cmp_gt_i32_e32 vcc, 0, v54
	v_not_b32_e32 v138, v55
	v_or_b32_e32 v139, 0x80000000, v55
	v_cndmask_b32_e32 v183, v137, v136, vcc
	v_cmp_gt_i32_e32 vcc, 0, v55
	v_not_b32_e32 v140, v56
	v_or_b32_e32 v141, 0x80000000, v56
	v_cndmask_b32_e32 v182, v139, v138, vcc
	v_cmp_gt_i32_e32 vcc, 0, v56
	v_not_b32_e32 v162, v57
	v_or_b32_e32 v163, 0x80000000, v57
	v_cndmask_b32_e32 v179, v141, v140, vcc
	v_cmp_gt_i32_e32 vcc, 0, v57
	v_not_b32_e32 v164, v58
	v_or_b32_e32 v165, 0x80000000, v58
	v_cndmask_b32_e32 v175, v163, v162, vcc
	v_cmp_gt_i32_e32 vcc, 0, v58
	v_lshlrev_b32_e32 v62, 2, v10
	v_mov_b32_e32 v63, v1
	v_not_b32_e32 v166, v59
	v_or_b32_e32 v167, 0x80000000, v59
	v_cndmask_b32_e32 v172, v165, v164, vcc
	v_cmp_gt_i32_e32 vcc, 0, v59
	v_lshl_add_u64 v[40:41], s[0:1], 0, v[62:63]
	v_not_b32_e32 v168, v60
	v_or_b32_e32 v169, 0x80000000, v60
	v_cndmask_b32_e32 v170, v167, v166, vcc
	v_cmp_gt_i32_e32 vcc, 0, v60
	flat_load_dword v135, v[40:41]
	v_lshlrev_b32_e32 v60, 2, v12
	v_mov_b32_e32 v61, v1
	v_lshl_add_u64 v[40:41], s[0:1], 0, v[60:61]
	v_lshlrev_b32_e32 v58, 2, v14
	v_mov_b32_e32 v59, v1
	flat_load_dword v136, v[40:41]
	v_lshl_add_u64 v[40:41], s[0:1], 0, v[58:59]
	v_lshlrev_b32_e32 v56, 2, v16
	v_mov_b32_e32 v57, v1
	flat_load_dword v137, v[40:41]
	v_lshl_add_u64 v[40:41], s[0:1], 0, v[56:57]
	flat_load_dword v138, v[40:41]
	v_lshlrev_b32_e32 v54, 2, v18
	v_mov_b32_e32 v55, v1
	v_lshl_add_u64 v[40:41], s[0:1], 0, v[54:55]
	flat_load_dword v139, v[40:41]
	v_lshlrev_b32_e32 v52, 2, v20
	v_mov_b32_e32 v53, v1
	v_lshl_add_u64 v[40:41], s[0:1], 0, v[52:53]
	v_lshlrev_b32_e32 v50, 2, v22
	v_mov_b32_e32 v51, v1
	flat_load_dword v140, v[40:41]
	v_lshl_add_u64 v[40:41], s[0:1], 0, v[50:51]
	v_lshlrev_b32_e32 v48, 2, v24
	v_mov_b32_e32 v49, v1
	v_cndmask_b32_e32 v167, v169, v168, vcc
	v_not_b32_e32 v42, v128
	v_or_b32_e32 v43, 0x80000000, v128
	v_cmp_gt_i32_e32 vcc, 0, v128
	flat_load_dword v141, v[40:41]
	v_lshl_add_u64 v[40:41], s[0:1], 0, v[48:49]
	v_lshlrev_b32_e32 v46, 2, v26
	v_mov_b32_e32 v47, v1
	v_cndmask_b32_e32 v169, v43, v42, vcc
	v_not_b32_e32 v42, v129
	v_or_b32_e32 v43, 0x80000000, v129
	v_cmp_gt_i32_e32 vcc, 0, v129
	flat_load_dword v162, v[40:41]
	v_lshl_add_u64 v[40:41], s[0:1], 0, v[46:47]
	v_cndmask_b32_e32 v174, v43, v42, vcc
	v_not_b32_e32 v42, v130
	v_or_b32_e32 v43, 0x80000000, v130
	flat_load_dword v190, v[40:41]
	v_lshlrev_b32_e32 v44, 2, v28
	v_mov_b32_e32 v45, v1
	v_cmp_gt_i32_e32 vcc, 0, v130
	v_lshl_add_u64 v[40:41], s[0:1], 0, v[44:45]
	flat_load_dword v191, v[40:41]
	v_cndmask_b32_e32 v178, v43, v42, vcc
	v_lshlrev_b32_e32 v42, 2, v30
	v_mov_b32_e32 v43, v1
	v_lshl_add_u64 v[40:41], s[0:1], 0, v[42:43]
	flat_load_dword v192, v[40:41]
	v_lshlrev_b32_e32 v40, 2, v32
	v_mov_b32_e32 v41, v1
	v_lshl_add_u64 v[128:129], s[0:1], 0, v[40:41]
	s_add_u32 s0, s12, 0x2000
	flat_load_dword v193, v[128:129]
	s_addc_u32 s1, s13, 0
	v_lshl_add_u64 v[128:129], s[0:1], 0, v[0:1]
	v_not_b32_e32 v130, v131
	v_or_b32_e32 v163, 0x80000000, v131
	flat_load_dword v194, v[128:129]
	v_cmp_gt_i32_e32 vcc, 0, v131
	v_not_b32_e32 v128, v132
	v_or_b32_e32 v129, 0x80000000, v132
	v_cndmask_b32_e32 v181, v163, v130, vcc
	v_cmp_gt_i32_e32 vcc, 0, v132
	v_not_b32_e32 v130, v133
	v_or_b32_e32 v132, 0x80000000, v134
	v_cndmask_b32_e32 v180, v129, v128, vcc
	v_lshl_add_u64 v[128:129], s[0:1], 0, v[38:39]
	flat_load_dword v131, v[128:129]
	v_or_b32_e32 v128, 0x80000000, v133
	v_cmp_gt_i32_e32 vcc, 0, v133
	s_nop 1
	v_cndmask_b32_e32 v177, v128, v130, vcc
	v_not_b32_e32 v130, v134
	v_lshl_add_u64 v[128:129], s[0:1], 0, v[36:37]
	v_cmp_gt_i32_e32 vcc, 0, v134
	flat_load_dword v133, v[128:129]
	s_waitcnt vmcnt(0) lgkmcnt(0)
; DI unsigned f2key(float f) { const unsigned u = __float_as_uint(f); return (u & 0x80000000u) ? ~u : (u | 0x80000000u); }
; template <int NV>
; DI void topk_row(const float* row, int s, LAS int* lst, int lane) {
;     ...
;     for (int jo = 0; jo < NV / 16; ++jo) { const float* rb = row + jo * 1024;
; #pragma unroll
;         for (int ji = 0; ji < 16; ++ji) { const int j = jo * 16 + ji; const unsigned u = f2key(rb[ji * 64 + lane]); key[j] = (j * 64 + lane <= s) ? u : 0u; } }
	v_not_b32_e32 v128, v135
	v_cndmask_b32_e32 v176, v132, v130, vcc
	v_or_b32_e32 v129, 0x80000000, v135
	v_cmp_gt_i32_e32 vcc, 0, v135
	v_not_b32_e32 v130, v136
	v_or_b32_e32 v134, 0x80000000, v137
	v_cndmask_b32_e32 v173, v129, v128, vcc
	v_lshl_add_u64 v[128:129], s[0:1], 0, v[34:35]
	flat_load_dword v132, v[128:129]
	v_or_b32_e32 v128, 0x80000000, v136
	v_cmp_gt_i32_e32 vcc, 0, v136
	s_nop 1
	v_cndmask_b32_e32 v171, v128, v130, vcc
	v_not_b32_e32 v130, v137
	v_lshl_add_u64 v[128:129], s[0:1], 0, v[62:63]
	v_cmp_gt_i32_e32 vcc, 0, v137
	flat_load_dword v195, v[128:129]
	v_not_b32_e32 v128, v138
	v_cndmask_b32_e32 v168, v134, v130, vcc
	v_or_b32_e32 v129, 0x80000000, v138
	v_cmp_gt_i32_e32 vcc, 0, v138
	v_not_b32_e32 v130, v139
	v_or_b32_e32 v134, 0x80000000, v140
	v_cndmask_b32_e32 v166, v129, v128, vcc
	v_lshl_add_u64 v[128:129], s[0:1], 0, v[60:61]
	flat_load_dword v196, v[128:129]
	v_or_b32_e32 v128, 0x80000000, v139
	v_cmp_gt_i32_e32 vcc, 0, v139
	s_nop 1
	v_cndmask_b32_e32 v165, v128, v130, vcc
	v_lshl_add_u64 v[128:129], s[0:1], 0, v[58:59]
	flat_load_dword v197, v[128:129]
	v_not_b32_e32 v130, v140
	v_cmp_gt_i32_e32 vcc, 0, v140
	v_not_b32_e32 v128, v141
	v_or_b32_e32 v129, 0x80000000, v141
	v_cndmask_b32_e32 v164, v134, v130, vcc
	v_cmp_gt_i32_e32 vcc, 0, v141
	v_not_b32_e32 v130, v162
	v_or_b32_e32 v134, 0x80000000, v162
	v_cndmask_b32_e32 v163, v129, v128, vcc
	v_lshl_add_u64 v[128:129], s[0:1], 0, v[56:57]
	v_cmp_gt_i32_e32 vcc, 0, v162
	flat_load_dword v198, v[128:129]
	v_not_b32_e32 v128, v190
	v_cndmask_b32_e32 v162, v134, v130, vcc
	v_or_b32_e32 v129, 0x80000000, v190
	v_cmp_gt_i32_e32 vcc, 0, v190
	v_not_b32_e32 v130, v191
	s_nop 0
	v_cndmask_b32_e32 v141, v129, v128, vcc
	v_lshl_add_u64 v[128:129], s[0:1], 0, v[54:55]
	flat_load_dword v190, v[128:129]
	v_or_b32_e32 v128, 0x80000000, v191
	v_cmp_gt_i32_e32 vcc, 0, v191
	s_nop 1
	v_cndmask_b32_e32 v140, v128, v130, vcc
	v_lshl_add_u64 v[128:129], s[0:1], 0, v[52:53]
	v_not_b32_e32 v130, v192
	flat_load_dword v191, v[128:129]
	v_or_b32_e32 v128, 0x80000000, v192
	v_cmp_gt_i32_e32 vcc, 0, v192
	v_or_b32_e32 v129, 0x80000000, v193
	s_nop 0
	v_cndmask_b32_e32 v139, v128, v130, vcc
	v_not_b32_e32 v128, v193
	v_cmp_gt_i32_e32 vcc, 0, v193
	v_not_b32_e32 v130, v194
	s_nop 0
	v_cndmask_b32_e32 v138, v129, v128, vcc
	v_lshl_add_u64 v[128:129], s[0:1], 0, v[50:51]
	flat_load_dword v192, v[128:129]
	v_or_b32_e32 v128, 0x80000000, v194
	v_cmp_gt_i32_e32 vcc, 0, v194
	s_nop 1
	v_cndmask_b32_e32 v128, v128, v130, vcc
	v_cmp_lt_u32_e32 vcc, s2, v161
	v_not_b32_e32 v130, v131
	s_movk_i32 s2, 0x83f
	v_cndmask_b32_e32 v137, 0, v128, vcc
	v_lshl_add_u64 v[128:129], s[0:1], 0, v[48:49]
	flat_load_dword v193, v[128:129]
	v_or_b32_e32 v128, 0x80000000, v131
	v_cmp_gt_i32_e32 vcc, 0, v131
	v_or_b32_e32 v131, 0x80000000, v133
	s_nop 0
	v_cndmask_b32_e32 v128, v128, v130, vcc
	v_cmp_lt_u32_e32 vcc, s2, v161
	v_not_b32_e32 v130, v133
	s_movk_i32 s2, 0x87f
	v_cndmask_b32_e32 v136, 0, v128, vcc
	v_lshl_add_u64 v[128:129], s[0:1], 0, v[46:47]
	flat_load_dword v194, v[128:129]
	v_cmp_gt_i32_e32 vcc, 0, v133
	s_nop 1
	v_cndmask_b32_e32 v128, v131, v130, vcc
	v_cmp_lt_u32_e32 vcc, s2, v161
	s_waitcnt vmcnt(0) lgkmcnt(0)
	v_not_b32_e32 v130, v132
	v_or_b32_e32 v131, 0x80000000, v132
	v_cndmask_b32_e32 v135, 0, v128, vcc
	v_lshl_add_u64 v[128:129], s[0:1], 0, v[44:45]
	v_cmp_gt_i32_e32 vcc, 0, v132
	s_movk_i32 s2, 0x8bf
	flat_load_dword v199, v[128:129]
	v_cndmask_b32_e32 v128, v131, v130, vcc
	v_cmp_lt_u32_e32 vcc, s2, v161
	v_or_b32_e32 v129, 0x80000000, v195
	s_movk_i32 s2, 0x8ff
	v_cndmask_b32_e32 v134, 0, v128, vcc
	v_not_b32_e32 v128, v195
	v_cmp_gt_i32_e32 vcc, 0, v195
	s_nop 1
	v_cndmask_b32_e32 v130, v129, v128, vcc
	v_lshl_add_u64 v[128:129], s[0:1], 0, v[42:43]
	v_cmp_lt_u32_e32 vcc, s2, v161
	flat_load_dword v195, v[128:129]
	v_not_b32_e32 v128, v196
	v_cndmask_b32_e32 v133, 0, v130, vcc
	v_or_b32_e32 v129, 0x80000000, v196
	v_cmp_gt_i32_e32 vcc, 0, v196
	s_nop 1
	v_cndmask_b32_e32 v130, v129, v128, vcc
	v_lshl_add_u64 v[128:129], s[0:1], 0, v[40:41]
	s_movk_i32 s0, 0x93f
	v_cmp_lt_u32_e32 vcc, s0, v161
	s_add_u32 s0, s12, 0x3000
	flat_load_dword v196, v[128:129]
	s_addc_u32 s1, s13, 0
	v_lshl_add_u64 v[38:39], s[0:1], 0, v[38:39]
	v_cndmask_b32_e32 v131, 0, v130, vcc
	v_cmp_gt_i32_e32 vcc, 0, v197
	flat_load_dword v38, v[38:39]
	v_not_b32_e32 v128, v197
	v_or_b32_e32 v129, 0x80000000, v197
	v_cndmask_b32_e32 v130, v129, v128, vcc
	v_lshl_add_u64 v[128:129], s[0:1], 0, v[0:1]
	flat_load_dword v0, v[128:129]
	v_cmp_lt_u32_e32 vcc, s22, v161
	v_not_b32_e32 v128, v198
	v_or_b32_e32 v129, 0x80000000, v198
	v_cndmask_b32_e32 v132, 0, v130, vcc
	v_cmp_gt_i32_e32 vcc, 0, v198
	v_lshl_add_u64 v[36:37], s[0:1], 0, v[36:37]
	flat_load_dword v36, v[36:37]
	v_cndmask_b32_e32 v128, v129, v128, vcc
	v_cmp_lt_u32_e32 vcc, s23, v161
	v_not_b32_e32 v39, v190
	v_or_b32_e32 v37, 0x80000000, v191
	v_cndmask_b32_e32 v130, 0, v128, vcc
	v_or_b32_e32 v128, 0x80000000, v190
	v_cmp_gt_i32_e32 vcc, 0, v190
	v_lshl_add_u64 v[34:35], s[0:1], 0, v[34:35]
	v_or_b32_e32 v190, 0x80000000, v192
	v_cndmask_b32_e32 v39, v128, v39, vcc
	v_cmp_lt_u32_e32 vcc, s24, v161
	s_nop 1
	v_cndmask_b32_e32 v128, 0, v39, vcc
	v_not_b32_e32 v39, v191
	v_cmp_gt_i32_e32 vcc, 0, v191
	s_nop 1
	v_cndmask_b32_e32 v37, v37, v39, vcc
	flat_load_dword v39, v[34:35]
	v_cmp_lt_u32_e32 vcc, s25, v161
	v_lshl_add_u64 v[34:35], s[0:1], 0, v[62:63]
	flat_load_dword v63, v[34:35]
	v_cndmask_b32_e32 v129, 0, v37, vcc
	v_not_b32_e32 v37, v192
	v_cmp_gt_i32_e32 vcc, 0, v192
	s_nop 1
	v_cndmask_b32_e32 v34, v190, v37, vcc
	v_cmp_lt_u32_e32 vcc, s26, v161
	v_not_b32_e32 v37, v193
	s_nop 0
	v_cndmask_b32_e32 v62, 0, v34, vcc
	v_lshl_add_u64 v[34:35], s[0:1], 0, v[60:61]
	flat_load_dword v60, v[34:35]
	v_or_b32_e32 v34, 0x80000000, v193
	v_cmp_gt_i32_e32 vcc, 0, v193
	v_or_b32_e32 v61, 0x80000000, v194
	s_nop 0
	v_cndmask_b32_e32 v37, v34, v37, vcc
	v_lshl_add_u64 v[34:35], s[0:1], 0, v[58:59]
	flat_load_dword v59, v[34:35]
	v_cmp_lt_u32_e32 vcc, s27, v161
	v_lshl_add_u64 v[34:35], s[0:1], 0, v[56:57]
	flat_load_dword v57, v[34:35]
	v_cndmask_b32_e32 v58, 0, v37, vcc
	v_not_b32_e32 v37, v194
	v_cmp_gt_i32_e32 vcc, 0, v194
	s_nop 1
	v_cndmask_b32_e32 v34, v61, v37, vcc
	v_cmp_lt_u32_e32 vcc, s28, v161
	s_waitcnt vmcnt(0) lgkmcnt(0)
; DI unsigned f2key(float f) { const unsigned u = __float_as_uint(f); return (u & 0x80000000u) ? ~u : (u | 0x80000000u); }
; template <int NV>
; DI void topk_row(const float* row, int s, LAS int* lst, int lane) {
;     ...
;     for (int jo = 0; jo < NV / 16; ++jo) { const float* rb = row + jo * 1024;
; #pragma unroll
;         for (int ji = 0; ji < 16; ++ji) { const int j = jo * 16 + ji; const unsigned u = f2key(rb[ji * 64 + lane]); key[j] = (j * 64 + lane <= s) ? u : 0u; } }
	v_not_b32_e32 v37, v199
	v_cndmask_b32_e32 v56, 0, v34, vcc
	v_lshl_add_u64 v[34:35], s[0:1], 0, v[54:55]
	flat_load_dword v54, v[34:35]
	v_or_b32_e32 v34, 0x80000000, v199
	v_cmp_gt_i32_e32 vcc, 0, v199
	v_or_b32_e32 v55, 0x80000000, v195
	s_nop 0
	v_cndmask_b32_e32 v37, v34, v37, vcc
	v_lshl_add_u64 v[34:35], s[0:1], 0, v[52:53]
	flat_load_dword v53, v[34:35]
	v_cmp_lt_u32_e32 vcc, s29, v161
	v_lshl_add_u64 v[34:35], s[0:1], 0, v[50:51]
	flat_load_dword v61, v[34:35]
	v_cndmask_b32_e32 v52, 0, v37, vcc
	v_not_b32_e32 v37, v195
	v_cmp_gt_i32_e32 vcc, 0, v195
	s_nop 1
	v_cndmask_b32_e32 v34, v55, v37, vcc
	v_cmp_lt_u32_e32 vcc, s30, v161
	v_not_b32_e32 v37, v196
	s_nop 0
	v_cndmask_b32_e32 v50, 0, v34, vcc
	v_lshl_add_u64 v[34:35], s[0:1], 0, v[48:49]
	flat_load_dword v55, v[34:35]
	v_or_b32_e32 v34, 0x80000000, v196
	v_cmp_gt_i32_e32 vcc, 0, v196
	s_nop 1
	v_cndmask_b32_e32 v37, v34, v37, vcc
	v_lshl_add_u64 v[34:35], s[0:1], 0, v[46:47]
	flat_load_dword v190, v[34:35]
	v_cmp_lt_u32_e32 vcc, s31, v161
	v_lshl_add_u64 v[34:35], s[0:1], 0, v[44:45]
	v_or_b32_e32 v46, 0x80000000, v0
	v_cndmask_b32_e32 v49, 0, v37, vcc
	v_not_b32_e32 v37, v0
	flat_load_dword v191, v[34:35]
	v_cmp_gt_i32_e32 vcc, 0, v0
	v_lshl_add_u64 v[34:35], s[0:1], 0, v[42:43]
	flat_load_dword v192, v[34:35]
	v_cndmask_b32_e32 v0, v46, v37, vcc
	v_cmp_lt_u32_e32 vcc, s36, v161
	v_or_b32_e32 v34, 0x80000000, v38
	s_nop 0
	v_cndmask_b32_e32 v48, 0, v0, vcc
	v_not_b32_e32 v0, v38
	v_cmp_gt_i32_e32 vcc, 0, v38
	s_nop 1
	v_cndmask_b32_e32 v0, v34, v0, vcc
	v_lshl_add_u64 v[34:35], s[0:1], 0, v[40:41]
	flat_load_dword v34, v[34:35]
	v_cmp_lt_u32_e32 vcc, s37, v161
	v_or_b32_e32 v35, 0x80000000, v36
	s_nop 0
	v_cndmask_b32_e32 v51, 0, v0, vcc
	v_not_b32_e32 v0, v36
	v_cmp_gt_i32_e32 vcc, 0, v36
	s_nop 1
	v_cndmask_b32_e32 v0, v35, v0, vcc
	v_cmp_lt_u32_e32 vcc, s38, v161
	v_or_b32_e32 v35, 0x80000000, v39
	s_nop 0
	v_cndmask_b32_e32 v47, 0, v0, vcc
	v_not_b32_e32 v0, v39
	v_cmp_gt_i32_e32 vcc, 0, v39
	s_nop 1
	v_cndmask_b32_e32 v0, v35, v0, vcc
	v_cmp_lt_u32_e32 vcc, s39, v161
	v_or_b32_e32 v35, 0x80000000, v63
	s_nop 0
	v_cndmask_b32_e32 v46, 0, v0, vcc
	v_not_b32_e32 v0, v63
	v_cmp_gt_i32_e32 vcc, 0, v63
	s_nop 1
	v_cndmask_b32_e32 v0, v35, v0, vcc
	v_cmp_lt_u32_e32 vcc, s40, v161
	v_or_b32_e32 v35, 0x80000000, v60
	s_nop 0
	v_cndmask_b32_e32 v45, 0, v0, vcc
	v_not_b32_e32 v0, v60
	v_cmp_gt_i32_e32 vcc, 0, v60
	s_nop 1
	v_cndmask_b32_e32 v0, v35, v0, vcc
	v_cmp_lt_u32_e32 vcc, s41, v161
	v_or_b32_e32 v35, 0x80000000, v59
	s_nop 0
	v_cndmask_b32_e32 v44, 0, v0, vcc
	v_not_b32_e32 v0, v59
	v_cmp_gt_i32_e32 vcc, 0, v59
	s_nop 1
	v_cndmask_b32_e32 v0, v35, v0, vcc
	v_cmp_lt_u32_e32 vcc, s42, v161
	v_or_b32_e32 v35, 0x80000000, v57
	s_nop 0
	v_cndmask_b32_e32 v43, 0, v0, vcc
	v_not_b32_e32 v0, v57
	v_cmp_gt_i32_e32 vcc, 0, v57
	s_nop 1
	v_cndmask_b32_e32 v0, v35, v0, vcc
	v_cmp_lt_u32_e32 vcc, s43, v161
	s_waitcnt vmcnt(0) lgkmcnt(0)
; DI unsigned f2key(float f) { const unsigned u = __float_as_uint(f); return (u & 0x80000000u) ? ~u : (u | 0x80000000u); }
; template <int NV>
; DI void topk_row(const float* row, int s, LAS int* lst, int lane) {
;     ...
;         for (int ji = 0; ji < 16; ++ji) { const int j = jo * 16 + ji; const unsigned u = f2key(rb[ji * 64 + lane]); key[j] = (j * 64 + lane <= s) ? u : 0u; } }
;     unsigned T = 0u;
; #pragma unroll 1
;     ...
;         const unsigned cand = T | (1u << bit); int c = 0;
; #pragma unroll
;         for (int j = 0; j < NV; ++j) asm volatile("v_cmp_le_u32 vcc, %2, %1\n\tv_addc_co_u32 %0, vcc, 0, %0, vcc" : "+v"(c) : "v"(key[j]), "s"(cand) : "vcc");
;         const int tot = wave_sum_i(c);
;         if (tot >= 256) T = cand;
;         if (tot == 256) break;
	v_or_b32_e32 v35, 0x80000000, v54
	v_cndmask_b32_e32 v42, 0, v0, vcc
	v_not_b32_e32 v0, v54
	v_cmp_gt_i32_e32 vcc, 0, v54
	s_nop 1
	v_cndmask_b32_e32 v0, v35, v0, vcc
	v_cmp_lt_u32_e32 vcc, s44, v161
	v_or_b32_e32 v35, 0x80000000, v53
	s_nop 0
	v_cndmask_b32_e32 v41, 0, v0, vcc
	v_not_b32_e32 v0, v53
	v_cmp_gt_i32_e32 vcc, 0, v53
	v_or_b32_e32 v53, 0x80000000, v34
	s_nop 0
	v_cndmask_b32_e32 v0, v35, v0, vcc
	v_cmp_lt_u32_e32 vcc, s45, v161
	v_or_b32_e32 v35, 0x80000000, v61
	s_nop 0
	v_cndmask_b32_e32 v40, 0, v0, vcc
	v_not_b32_e32 v0, v61
	v_cmp_gt_i32_e32 vcc, 0, v61
	s_nop 1
	v_cndmask_b32_e32 v0, v35, v0, vcc
	v_cmp_lt_u32_e32 vcc, s46, v161
	v_or_b32_e32 v35, 0x80000000, v55
	s_nop 0
	v_cndmask_b32_e32 v39, 0, v0, vcc
	v_not_b32_e32 v0, v55
	v_cmp_gt_i32_e32 vcc, 0, v55
	s_nop 1
	v_cndmask_b32_e32 v0, v35, v0, vcc
	v_cmp_lt_u32_e32 vcc, s47, v161
	v_or_b32_e32 v35, 0x80000000, v190
	s_nop 0
	v_cndmask_b32_e32 v38, 0, v0, vcc
	v_not_b32_e32 v0, v190
	v_cmp_gt_i32_e32 vcc, 0, v190
	s_nop 1
	v_cndmask_b32_e32 v0, v35, v0, vcc
	v_cmp_lt_u32_e32 vcc, s48, v161
	v_or_b32_e32 v35, 0x80000000, v191
	s_nop 0
	v_cndmask_b32_e32 v37, 0, v0, vcc
	v_not_b32_e32 v0, v191
	v_cmp_gt_i32_e32 vcc, 0, v191
	s_nop 1
	v_cndmask_b32_e32 v0, v35, v0, vcc
	v_cmp_lt_u32_e32 vcc, s49, v161
	v_or_b32_e32 v35, 0x80000000, v192
	s_nop 0
	v_cndmask_b32_e32 v36, 0, v0, vcc
	v_not_b32_e32 v0, v192
	v_cmp_gt_i32_e32 vcc, 0, v192
	s_nop 1
	v_cndmask_b32_e32 v0, v35, v0, vcc
	v_cmp_lt_u32_e32 vcc, s50, v161
	s_nop 1
	v_cndmask_b32_e32 v35, 0, v0, vcc
	v_not_b32_e32 v0, v34
	v_cmp_gt_i32_e32 vcc, 0, v34
	v_mov_b32_e32 v34, 0
	s_nop 0
	v_cndmask_b32_e32 v0, v53, v0, vcc
	v_cmp_lt_u32_e32 vcc, s51, v161
	v_mov_b32_e32 v53, 31
	s_nop 0
	v_cndmask_b32_e32 v0, 0, v0, vcc
	v_max_u32_e32 v54, v189, v185
	v_max_u32_e32 v55, v188, v184
	v_max_u32_e32 v34, v187, v183
	v_max_u32_e32 v53, v186, v182
	v_max_u32_e32 v54, v54, v179
	v_max_u32_e32 v55, v55, v175
	v_max_u32_e32 v34, v34, v172
	v_max_u32_e32 v53, v53, v170
	v_max_u32_e32 v54, v54, v167
	v_max_u32_e32 v55, v55, v169
	v_max_u32_e32 v34, v34, v174
	v_max_u32_e32 v53, v53, v178
	v_max_u32_e32 v54, v54, v181
	v_max_u32_e32 v55, v55, v180
	v_max_u32_e32 v34, v34, v177
	v_max_u32_e32 v53, v53, v176
	v_max_u32_e32 v54, v54, v173
	v_max_u32_e32 v55, v55, v171
	v_max_u32_e32 v34, v34, v168
	v_max_u32_e32 v53, v53, v166
	v_max_u32_e32 v54, v54, v165
	v_max_u32_e32 v55, v55, v164
	v_max_u32_e32 v34, v34, v163
	v_max_u32_e32 v53, v53, v162
	v_max_u32_e32 v54, v54, v141
	v_max_u32_e32 v55, v55, v140
	v_max_u32_e32 v34, v34, v139
	v_max_u32_e32 v53, v53, v138
	v_max_u32_e32 v54, v54, v137
	v_max_u32_e32 v55, v55, v136
	v_max_u32_e32 v34, v34, v135
	v_max_u32_e32 v53, v53, v134
	v_max_u32_e32 v54, v54, v133
	v_max_u32_e32 v55, v55, v131
	v_max_u32_e32 v34, v34, v132
	v_max_u32_e32 v53, v53, v130
	v_max_u32_e32 v54, v54, v128
	v_max_u32_e32 v55, v55, v129
	v_max_u32_e32 v34, v34, v62
	v_max_u32_e32 v53, v53, v58
	v_max_u32_e32 v54, v54, v56
	v_max_u32_e32 v55, v55, v52
	v_max_u32_e32 v34, v34, v50
	v_max_u32_e32 v53, v53, v49
	v_max_u32_e32 v54, v54, v48
	v_max_u32_e32 v55, v55, v51
	v_max_u32_e32 v34, v34, v47
	v_max_u32_e32 v53, v53, v46
	v_max_u32_e32 v54, v54, v45
	v_max_u32_e32 v55, v55, v44
	v_max_u32_e32 v34, v34, v43
	v_max_u32_e32 v53, v53, v42
	v_max_u32_e32 v54, v54, v41
	v_max_u32_e32 v55, v55, v40
	v_max_u32_e32 v34, v34, v39
	v_max_u32_e32 v53, v53, v38
	v_max_u32_e32 v54, v54, v37
	v_max_u32_e32 v55, v55, v36
	v_max_u32_e32 v34, v34, v35
	v_max_u32_e32 v53, v53, v0
	v_max3_u32 v255, v54, v55, v34
	v_min3_u32 v54, v54, v55, v34
	v_max_u32_e32 v255, v255, v53
	v_min_u32_e32 v54, v54, v53
	s_nop 1
	v_max_u32_dpp v255, v255, v255 quad_perm:[1,0,3,2] row_mask:0xf bank_mask:0xf bound_ctrl:1
	v_min_u32_dpp v54, v54, v54 quad_perm:[1,0,3,2] row_mask:0xf bank_mask:0xf bound_ctrl:1
	s_nop 1
	v_max_u32_dpp v255, v255, v255 quad_perm:[2,3,0,1] row_mask:0xf bank_mask:0xf bound_ctrl:1
	v_min_u32_dpp v54, v54, v54 quad_perm:[2,3,0,1] row_mask:0xf bank_mask:0xf bound_ctrl:1
	s_nop 1
	v_max_u32_dpp v255, v255, v255 row_half_mirror row_mask:0xf bank_mask:0xf bound_ctrl:1
	v_min_u32_dpp v54, v54, v54 row_half_mirror row_mask:0xf bank_mask:0xf bound_ctrl:1
	s_nop 1
	v_max_u32_dpp v255, v255, v255 row_mirror row_mask:0xf bank_mask:0xf bound_ctrl:1
	v_min_u32_dpp v54, v54, v54 row_mirror row_mask:0xf bank_mask:0xf bound_ctrl:1
	s_nop 1
	v_readlane_b32 s0, v255, 0
	v_readlane_b32 s1, v255, 16
	s_max_u32 s0, s0, s1
	v_readlane_b32 s1, v255, 32
	s_max_u32 s0, s0, s1
	v_readlane_b32 s1, v255, 48
	s_max_u32 s100, s0, s1
	v_readlane_b32 s0, v54, 0
	v_readlane_b32 s1, v54, 16
	s_min_u32 s0, s0, s1
	v_readlane_b32 s1, v54, 32
	s_min_u32 s0, s0, s1
	v_readlane_b32 s1, v54, 48
	s_min_u32 s101, s0, s1
	s_xor_b32 s0, s100, s101
	s_max_u32 s0, s0, 1
	s_flbit_i32_b32 s1, s0
	s_sub_u32 s1, 31, s1
	s_lshl_b32 s0, 1, s1
	s_lshl_b32 s0, s0, 1
	s_sub_u32 s0, s0, 1
	s_andn2_b32 s0, s100, s0
	v_mov_b32_e32 v34, s0
	v_mov_b32_e32 v53, s1

; DI unsigned f2key(float f) { const unsigned u = __float_as_uint(f); return (u & 0x80000000u) ? ~u : (u | 0x80000000u); }
; template <int NV>
; DI void topk_row(const float* row, int s, LAS int* lst, int lane) {
;     ...
;     for (int jo = 0; jo < NV / 16; ++jo) { const float* rb = row + jo * 1024;
; #pragma unroll
;         for (int ji = 0; ji < 16; ++ji) { const int j = jo * 16 + ji; const unsigned u = f2key(rb[ji * 64 + lane]); key[j] = (j * 64 + lane <= s) ? u : 0u; } }
.LBB0_3128:
	v_lshlrev_b32_e32 v0, 2, v2
	v_lshl_add_u64 v[34:35], s[12:13], 0, v[0:1]
	flat_load_dword v38, v[34:35]
	flat_load_dword v39, v[34:35] offset:256
	flat_load_dword v40, v[34:35] offset:512
	flat_load_dword v41, v[34:35] offset:768
	flat_load_dword v45, v[34:35] offset:1024
	flat_load_dword v46, v[34:35] offset:1280
	flat_load_dword v47, v[34:35] offset:1536
	flat_load_dword v52, v[34:35] offset:1792
	flat_load_dword v53, v[34:35] offset:2048
	flat_load_dword v54, v[34:35] offset:2304
	flat_load_dword v55, v[34:35] offset:2560
	flat_load_dword v56, v[34:35] offset:2816
	flat_load_dword v57, v[34:35] offset:3072
	s_add_u32 s0, s12, 0x1000
	s_addc_u32 s1, s13, 0
	flat_load_dword v58, v[34:35] offset:3328
	flat_load_dword v48, v[34:35] offset:3584
	flat_load_dword v51, v[34:35] offset:3840
	v_lshl_add_u64 v[34:35], s[0:1], 0, v[0:1]
	v_lshlrev_b32_e32 v0, 2, v4
	v_lshl_add_u64 v[36:37], s[0:1], 0, v[0:1]
	flat_load_dword v50, v[34:35]
	flat_load_dword v49, v[36:37]
	s_movk_i32 s2, 0xff
	s_waitcnt vmcnt(0) lgkmcnt(0)
	v_not_b32_e32 v0, v38
	v_or_b32_e32 v34, 0x80000000, v38
	v_cmp_gt_i32_e32 vcc, 0, v38
	v_not_b32_e32 v35, v39
	v_or_b32_e32 v36, 0x80000000, v39
	v_cndmask_b32_e32 v44, v34, v0, vcc
	v_cmp_gt_i32_e32 vcc, 0, v39
	v_not_b32_e32 v37, v40
	v_or_b32_e32 v42, 0x80000000, v40
	v_cndmask_b32_e32 v43, v36, v35, vcc
	v_cmp_gt_i32_e32 vcc, 0, v40
	v_not_b32_e32 v59, v41
	v_or_b32_e32 v60, 0x80000000, v41
	v_cndmask_b32_e32 v42, v42, v37, vcc
	v_cmp_gt_i32_e32 vcc, 0, v41
	v_not_b32_e32 v61, v45
	v_or_b32_e32 v62, 0x80000000, v45
	v_cndmask_b32_e32 v41, v60, v59, vcc
	v_cmp_gt_i32_e32 vcc, 0, v45
	v_not_b32_e32 v63, v46
	v_or_b32_e32 v128, 0x80000000, v46
	v_cndmask_b32_e32 v0, v62, v61, vcc
	v_cmp_gt_i32_e32 vcc, 0, v46
	v_not_b32_e32 v129, v47
	v_or_b32_e32 v130, 0x80000000, v47
	v_cndmask_b32_e32 v34, v128, v63, vcc
	v_cmp_gt_i32_e32 vcc, 0, v47
	v_not_b32_e32 v131, v52
	v_or_b32_e32 v132, 0x80000000, v52
	v_cndmask_b32_e32 v35, v130, v129, vcc
	v_cmp_gt_i32_e32 vcc, 0, v52
	v_not_b32_e32 v133, v53
	v_or_b32_e32 v134, 0x80000000, v53
	v_cndmask_b32_e32 v36, v132, v131, vcc
	v_cmp_gt_i32_e32 vcc, 0, v53
	v_not_b32_e32 v135, v54
	v_or_b32_e32 v136, 0x80000000, v54
	v_cndmask_b32_e32 v45, v134, v133, vcc
	v_cmp_gt_i32_e32 vcc, 0, v54
	v_not_b32_e32 v137, v55
	v_or_b32_e32 v138, 0x80000000, v55
	v_cndmask_b32_e32 v46, v136, v135, vcc
	v_cmp_gt_i32_e32 vcc, 0, v55
	v_not_b32_e32 v139, v56
	v_not_b32_e32 v54, v57
	v_cndmask_b32_e32 v47, v138, v137, vcc
	v_cmp_lt_u32_e32 vcc, s2, v161
	v_or_b32_e32 v55, 0x80000000, v57
	s_nop 0
	v_cndmask_b32_e32 v40, 0, v0, vcc
	v_cmp_lt_u32_e32 vcc, s52, v161
	v_lshlrev_b32_e32 v0, 2, v6
	s_nop 0
	v_cndmask_b32_e32 v39, 0, v34, vcc
	v_cmp_lt_u32_e32 vcc, s53, v161
	s_nop 1
	v_cndmask_b32_e32 v38, 0, v35, vcc
	v_cmp_lt_u32_e32 vcc, s54, v161
	s_nop 1
	v_cndmask_b32_e32 v37, 0, v36, vcc
	v_cmp_lt_u32_e32 vcc, s55, v161
	s_nop 1
	v_cndmask_b32_e32 v36, 0, v45, vcc
	v_cmp_lt_u32_e32 vcc, s56, v161
	v_or_b32_e32 v45, 0x80000000, v56
	s_nop 0
	v_cndmask_b32_e32 v35, 0, v46, vcc
	v_cmp_lt_u32_e32 vcc, s57, v161
	s_nop 1
	v_cndmask_b32_e32 v34, 0, v47, vcc
	v_lshl_add_u64 v[46:47], s[0:1], 0, v[0:1]
	flat_load_dword v52, v[46:47]
	v_lshlrev_b32_e32 v0, 2, v8
	v_lshl_add_u64 v[46:47], s[0:1], 0, v[0:1]
	flat_load_dword v53, v[46:47]
	v_lshlrev_b32_e32 v0, 2, v10
	v_cmp_gt_i32_e32 vcc, 0, v56
	v_lshl_add_u64 v[46:47], s[0:1], 0, v[0:1]
	flat_load_dword v56, v[46:47]
	v_cndmask_b32_e32 v45, v45, v139, vcc
	v_cmp_lt_u32_e32 vcc, s59, v161
	v_lshlrev_b32_e32 v0, 2, v12
	v_lshl_add_u64 v[46:47], s[0:1], 0, v[0:1]
	v_cndmask_b32_e32 v45, 0, v45, vcc
	v_cmp_gt_i32_e32 vcc, 0, v57
	flat_load_dword v59, v[46:47]
	v_lshlrev_b32_e32 v0, 2, v14
	v_cndmask_b32_e32 v54, v55, v54, vcc
	v_cmp_lt_u32_e32 vcc, s60, v161
	v_not_b32_e32 v47, v58
	v_or_b32_e32 v57, 0x80000000, v58
	v_cndmask_b32_e32 v46, 0, v54, vcc
	v_lshl_add_u64 v[54:55], s[0:1], 0, v[0:1]
	flat_load_dword v128, v[54:55]
	v_lshlrev_b32_e32 v0, 2, v16
	v_lshl_add_u64 v[54:55], s[0:1], 0, v[0:1]
	flat_load_dword v129, v[54:55]
	v_lshlrev_b32_e32 v0, 2, v18
	v_lshl_add_u64 v[54:55], s[0:1], 0, v[0:1]
	flat_load_dword v130, v[54:55]
	v_lshlrev_b32_e32 v0, 2, v20
	v_lshl_add_u64 v[54:55], s[0:1], 0, v[0:1]
	flat_load_dword v131, v[54:55]
	v_lshlrev_b32_e32 v0, 2, v22
	v_lshl_add_u64 v[54:55], s[0:1], 0, v[0:1]
	flat_load_dword v132, v[54:55]
	v_lshlrev_b32_e32 v0, 2, v24
	v_lshl_add_u64 v[54:55], s[0:1], 0, v[0:1]
	flat_load_dword v133, v[54:55]
	v_lshlrev_b32_e32 v0, 2, v26
	v_lshl_add_u64 v[54:55], s[0:1], 0, v[0:1]
	flat_load_dword v134, v[54:55]
	v_lshlrev_b32_e32 v0, 2, v28
	v_lshl_add_u64 v[54:55], s[0:1], 0, v[0:1]
	flat_load_dword v135, v[54:55]
	v_lshlrev_b32_e32 v0, 2, v30
	v_lshl_add_u64 v[54:55], s[0:1], 0, v[0:1]
	flat_load_dword v136, v[54:55]
	v_lshlrev_b32_e32 v0, 2, v32
	v_lshl_add_u64 v[54:55], s[0:1], 0, v[0:1]
	flat_load_dword v137, v[54:55]
	v_cmp_gt_i32_e32 vcc, 0, v58
	v_or_b32_e32 v58, 0x80000000, v48
	s_waitcnt vmcnt(0) lgkmcnt(0)
; DI unsigned f2key(float f) { const unsigned u = __float_as_uint(f); return (u & 0x80000000u) ? ~u : (u | 0x80000000u); }
; template <int NV>
; DI void topk_row(const float* row, int s, LAS int* lst, int lane) {
;     ...
;         for (int ji = 0; ji < 16; ++ji) { const int j = jo * 16 + ji; const unsigned u = f2key(rb[ji * 64 + lane]); key[j] = (j * 64 + lane <= s) ? u : 0u; } }
;     unsigned T = 0u;
; #pragma unroll 1
;     ...
;         const unsigned cand = T | (1u << bit); int c = 0;
; #pragma unroll
;         for (int j = 0; j < NV; ++j) asm volatile("v_cmp_le_u32 vcc, %2, %1\n\tv_addc_co_u32 %0, vcc, 0, %0, vcc" : "+v"(c) : "v"(key[j]), "s"(cand) : "vcc");
;         const int tot = wave_sum_i(c);
;         if (tot >= 256) T = cand;
;         if (tot == 256) break;
	v_not_b32_e32 v0, v52
	v_cndmask_b32_e32 v47, v57, v47, vcc
	v_cmp_lt_u32_e32 vcc, s61, v161
	v_not_b32_e32 v57, v48
	s_nop 0
	v_cndmask_b32_e32 v47, 0, v47, vcc
	v_cmp_gt_i32_e32 vcc, 0, v48
	s_nop 1
	v_cndmask_b32_e32 v48, v58, v57, vcc
	v_cmp_lt_u32_e32 vcc, s62, v161
	v_not_b32_e32 v57, v51
	v_or_b32_e32 v58, 0x80000000, v51
	v_cndmask_b32_e32 v48, 0, v48, vcc
	v_cmp_gt_i32_e32 vcc, 0, v51
	s_nop 1
	v_cndmask_b32_e32 v51, v58, v57, vcc
	v_cmp_lt_u32_e32 vcc, s63, v161
	v_not_b32_e32 v57, v50
	v_or_b32_e32 v58, 0x80000000, v50
	v_cndmask_b32_e32 v51, 0, v51, vcc
	v_cmp_gt_i32_e32 vcc, 0, v50
	s_nop 1
	v_cndmask_b32_e32 v50, v58, v57, vcc
	v_cmp_lt_u32_e32 vcc, s64, v161
	v_or_b32_e32 v58, 0x80000000, v49
	s_nop 0
	v_cndmask_b32_e32 v57, 0, v50, vcc
	v_not_b32_e32 v50, v49
	v_cmp_gt_i32_e32 vcc, 0, v49
	s_nop 1
	v_cndmask_b32_e32 v49, v58, v50, vcc
	v_cmp_lt_u32_e32 vcc, s65, v161
	s_nop 1
	v_cndmask_b32_e32 v63, 0, v49, vcc
	v_or_b32_e32 v49, 0x80000000, v52
	v_cmp_gt_i32_e32 vcc, 0, v52
	s_nop 1
	v_cndmask_b32_e32 v0, v49, v0, vcc
	v_cmp_lt_u32_e32 vcc, s66, v161
	v_or_b32_e32 v49, 0x80000000, v53
	s_nop 0
	v_cndmask_b32_e32 v62, 0, v0, vcc
	v_not_b32_e32 v0, v53
	v_cmp_gt_i32_e32 vcc, 0, v53
	s_nop 1
	v_cndmask_b32_e32 v0, v49, v0, vcc
	v_cmp_lt_u32_e32 vcc, s67, v161
	v_or_b32_e32 v49, 0x80000000, v56
	s_nop 0
	v_cndmask_b32_e32 v61, 0, v0, vcc
	v_not_b32_e32 v0, v56
	v_cmp_gt_i32_e32 vcc, 0, v56
	s_nop 1
	v_cndmask_b32_e32 v0, v49, v0, vcc
	v_cmp_lt_u32_e32 vcc, s68, v161
	v_or_b32_e32 v49, 0x80000000, v59
	s_nop 0
	v_cndmask_b32_e32 v60, 0, v0, vcc
	v_not_b32_e32 v0, v59
	v_cmp_gt_i32_e32 vcc, 0, v59
	s_nop 1
	v_cndmask_b32_e32 v0, v49, v0, vcc
	v_cmp_lt_u32_e32 vcc, s69, v161
	v_or_b32_e32 v49, 0x80000000, v128
	s_nop 0
	v_cndmask_b32_e32 v59, 0, v0, vcc
	v_not_b32_e32 v0, v128
	v_cmp_gt_i32_e32 vcc, 0, v128
	v_or_b32_e32 v128, 0x80000000, v136
	s_nop 0
	v_cndmask_b32_e32 v0, v49, v0, vcc
	v_cmp_lt_u32_e32 vcc, s70, v161
	v_or_b32_e32 v49, 0x80000000, v129
	s_nop 0
	v_cndmask_b32_e32 v58, 0, v0, vcc
	v_not_b32_e32 v0, v129
	v_cmp_gt_i32_e32 vcc, 0, v129
	v_or_b32_e32 v129, 0x80000000, v137
	s_nop 0
	v_cndmask_b32_e32 v0, v49, v0, vcc
	v_cmp_lt_u32_e32 vcc, s71, v161
	v_or_b32_e32 v49, 0x80000000, v130
	s_nop 0
	v_cndmask_b32_e32 v56, 0, v0, vcc
	v_not_b32_e32 v0, v130
	v_cmp_gt_i32_e32 vcc, 0, v130
	v_mov_b32_e32 v130, 31
	s_nop 0
	v_cndmask_b32_e32 v0, v49, v0, vcc
	v_cmp_lt_u32_e32 vcc, s72, v161
	v_or_b32_e32 v49, 0x80000000, v131
	s_nop 0
	v_cndmask_b32_e32 v55, 0, v0, vcc
	v_not_b32_e32 v0, v131
	v_cmp_gt_i32_e32 vcc, 0, v131
	s_nop 1
	v_cndmask_b32_e32 v0, v49, v0, vcc
	v_cmp_lt_u32_e32 vcc, s73, v161
	v_or_b32_e32 v49, 0x80000000, v132
	s_nop 0
	v_cndmask_b32_e32 v54, 0, v0, vcc
	v_not_b32_e32 v0, v132
	v_cmp_gt_i32_e32 vcc, 0, v132
	s_nop 1
	v_cndmask_b32_e32 v0, v49, v0, vcc
	v_cmp_lt_u32_e32 vcc, s74, v161
	v_or_b32_e32 v49, 0x80000000, v133
	s_nop 0
	v_cndmask_b32_e32 v53, 0, v0, vcc
	v_not_b32_e32 v0, v133
	v_cmp_gt_i32_e32 vcc, 0, v133
	s_nop 1
	v_cndmask_b32_e32 v0, v49, v0, vcc
	v_cmp_lt_u32_e32 vcc, s75, v161
	v_or_b32_e32 v49, 0x80000000, v134
	s_nop 0
	v_cndmask_b32_e32 v52, 0, v0, vcc
	v_not_b32_e32 v0, v134
	v_cmp_gt_i32_e32 vcc, 0, v134
	s_nop 1
	v_cndmask_b32_e32 v0, v49, v0, vcc
	v_cmp_lt_u32_e32 vcc, s76, v161
	v_or_b32_e32 v49, 0x80000000, v135
	s_nop 0
	v_cndmask_b32_e32 v50, 0, v0, vcc
	v_not_b32_e32 v0, v135
	v_cmp_gt_i32_e32 vcc, 0, v135
	s_nop 1
	v_cndmask_b32_e32 v0, v49, v0, vcc
	v_cmp_lt_u32_e32 vcc, s77, v161
	s_nop 1
	v_cndmask_b32_e32 v49, 0, v0, vcc
	v_not_b32_e32 v0, v136
	v_cmp_gt_i32_e32 vcc, 0, v136
	s_nop 1
	v_cndmask_b32_e32 v0, v128, v0, vcc
	v_cmp_lt_u32_e32 vcc, s78, v161
	v_not_b32_e32 v128, v137
	s_nop 0
	v_cndmask_b32_e32 v0, 0, v0, vcc
	v_cmp_gt_i32_e32 vcc, 0, v137
	s_nop 1
	v_cndmask_b32_e32 v128, v129, v128, vcc
	v_cmp_lt_u32_e32 vcc, s79, v161
	v_mov_b32_e32 v129, 0
	s_nop 0
	v_cndmask_b32_e32 v128, 0, v128, vcc
	v_max_u32_e32 v131, v44, v40
	v_max_u32_e32 v132, v43, v39
	v_max_u32_e32 v129, v42, v38
	v_max_u32_e32 v130, v41, v37
	v_max_u32_e32 v131, v131, v36
	v_max_u32_e32 v132, v132, v35
	v_max_u32_e32 v129, v129, v34
	v_max_u32_e32 v130, v130, v45
	v_max_u32_e32 v131, v131, v46
	v_max_u32_e32 v132, v132, v47
	v_max_u32_e32 v129, v129, v48
	v_max_u32_e32 v130, v130, v51
	v_max_u32_e32 v131, v131, v57
	v_max_u32_e32 v132, v132, v63
	v_max_u32_e32 v129, v129, v62
	v_max_u32_e32 v130, v130, v61
	v_max_u32_e32 v131, v131, v60
	v_max_u32_e32 v132, v132, v59
	v_max_u32_e32 v129, v129, v58
	v_max_u32_e32 v130, v130, v56
	v_max_u32_e32 v131, v131, v55
	v_max_u32_e32 v132, v132, v54
	v_max_u32_e32 v129, v129, v53
	v_max_u32_e32 v130, v130, v52
	v_max_u32_e32 v131, v131, v50
	v_max_u32_e32 v132, v132, v49
	v_max_u32_e32 v129, v129, v0
	v_max_u32_e32 v130, v130, v128
	v_max3_u32 v255, v131, v132, v129
	v_min3_u32 v131, v131, v132, v129
	v_max_u32_e32 v255, v255, v130
	v_min_u32_e32 v131, v131, v130
	s_nop 1
	v_max_u32_dpp v255, v255, v255 quad_perm:[1,0,3,2] row_mask:0xf bank_mask:0xf bound_ctrl:1
	v_min_u32_dpp v131, v131, v131 quad_perm:[1,0,3,2] row_mask:0xf bank_mask:0xf bound_ctrl:1
	s_nop 1
	v_max_u32_dpp v255, v255, v255 quad_perm:[2,3,0,1] row_mask:0xf bank_mask:0xf bound_ctrl:1
	v_min_u32_dpp v131, v131, v131 quad_perm:[2,3,0,1] row_mask:0xf bank_mask:0xf bound_ctrl:1
	s_nop 1
	v_max_u32_dpp v255, v255, v255 row_half_mirror row_mask:0xf bank_mask:0xf bound_ctrl:1
	v_min_u32_dpp v131, v131, v131 row_half_mirror row_mask:0xf bank_mask:0xf bound_ctrl:1
	s_nop 1
	v_max_u32_dpp v255, v255, v255 row_mirror row_mask:0xf bank_mask:0xf bound_ctrl:1
	v_min_u32_dpp v131, v131, v131 row_mirror row_mask:0xf bank_mask:0xf bound_ctrl:1
	s_nop 1
	v_readlane_b32 s0, v255, 0
	v_readlane_b32 s1, v255, 16
	s_max_u32 s0, s0, s1
	v_readlane_b32 s1, v255, 32
	s_max_u32 s0, s0, s1
	v_readlane_b32 s1, v255, 48
	s_max_u32 s100, s0, s1
	v_readlane_b32 s0, v131, 0
	v_readlane_b32 s1, v131, 16
	s_min_u32 s0, s0, s1
	v_readlane_b32 s1, v131, 32
	s_min_u32 s0, s0, s1
	v_readlane_b32 s1, v131, 48
	s_min_u32 s101, s0, s1
	s_xor_b32 s0, s100, s101
	s_max_u32 s0, s0, 1
	s_flbit_i32_b32 s1, s0
	s_sub_u32 s1, 31, s1
	s_lshl_b32 s0, 1, s1
	s_lshl_b32 s0, s0, 1
	s_sub_u32 s0, s0, 1
	s_andn2_b32 s0, s100, s0
	v_mov_b32_e32 v129, s0
	v_mov_b32_e32 v130, s1
